# gain vectors of the row phases fetched ahead of the store sequence: phase-0 pre-norm and final phase preload the eight gain quads into registers, post0 phase copies both gain vectors to LDS (removes l
# speedup vs baseline: 1.0112x; 1.0011x over previous
.LBB0_7:
	s_mov_b32 s38, s42
	s_cmp_lt_i32 s38, 6
	s_mov_b64 s[0:1], -1
	s_cbranch_scc1 .LBB0_173
	s_cmp_lt_i32 s38, 9
	s_cbranch_scc1 .LBB0_89
	s_cmp_lt_i32 s38, 11
	s_cbranch_scc1 .LBB0_40
	s_cmp_lt_i32 s38, 12
	s_cbranch_scc1 .LBB0_33
	s_cmp_eq_u32 s38, 12
	s_cbranch_scc0 .LBB0_32
	v_readfirstlane_b32 s2, v184
	v_readfirstlane_b32 s3, v185
	v_mov_b32_e32 v1, v189
	s_nop 0
	v_ashrrev_i32_e32 v0, 6, v1
	v_add_u32_e32 v0, s62, v0
	v_cmp_gt_i32_e32 vcc, s76, v0
	s_and_saveexec_b64 s[0:1], vcc
	s_cbranch_execz .LBB0_31
	v_and_b32_e32 v1, 63, v1
	v_cmp_lt_i32_e32 vcc, v228, v227
	v_lshlrev_b32_e32 v186, 4, v1
	v_lshlrev_b32_e32 v2, 3, v1
	v_cndmask_b32_e32 v1, v226, v228, vcc
	v_cmp_lt_i32_e32 vcc, v229, v227
	v_readlane_b32 s4, v254, 2
	v_mov_b32_e32 v3, v187
	v_lshlrev_b32_e32 v118, 2, v1
	v_cndmask_b32_e32 v1, v226, v229, vcc
	v_cmp_lt_i32_e32 vcc, v230, v227
	v_readlane_b32 s5, v254, 3
	v_lshl_add_u64 v[2:3], s[2:3], 0, v[2:3]
	s_mov_b64 s[2:3], 0x8000000
	s_waitcnt vmcnt(8)
	v_lshlrev_b32_e32 v124, 2, v1
	v_cndmask_b32_e32 v1, v226, v230, vcc
	v_cmp_lt_i32_e32 vcc, v231, v227
	v_lshl_add_u64 v[68:69], s[4:5], 0, v[186:187]
	v_lshl_add_u64 v[70:71], v[2:3], 0, s[2:3]
	v_lshlrev_b32_e32 v126, 2, v1
	v_cndmask_b32_e32 v1, v226, v231, vcc
	v_cmp_lt_i32_e32 vcc, v232, v227
	s_mov_b64 s[2:3], 0x1400
	s_waitcnt vmcnt(3)
	v_lshlrev_b32_e32 v146, 2, v1
	v_cndmask_b32_e32 v1, v226, v232, vcc
	v_cmp_lt_i32_e32 vcc, v233, v227
	v_lshl_add_u64 v[74:75], v[68:69], 0, s[2:3]
	s_mov_b64 s[2:3], 0x1800
	v_readlane_b32 s6, v254, 4
	v_readlane_b32 s7, v254, 5
	s_waitcnt vmcnt(2)
	v_lshlrev_b32_e32 v148, 2, v1
	v_cndmask_b32_e32 v1, v226, v233, vcc
	v_lshl_add_u64 v[76:77], v[68:69], 0, s[2:3]
	s_mov_b64 s[2:3], 0x1c00
	v_lshlrev_b32_e32 v180, 2, v1
	v_lshl_add_u64 v[72:73], v[68:69], 0, s[86:87]
	v_lshl_add_u64 v[78:79], v[68:69], 0, s[2:3]
	v_lshl_add_u64 v[80:81], s[6:7], 0, v[186:187]
	s_mov_b64 s[2:3], 0
	global_load_dwordx4 v[210:213], v[68:69], off
	global_load_dwordx4 v[214:217], v[68:69], off offset:1024
	global_load_dwordx4 v[218:221], v[68:69], off offset:2048
	global_load_dwordx4 v[222:225], v[68:69], off offset:3072
	global_load_dwordx4 v[234:237], v[72:73], off
	global_load_dwordx4 v[238:241], v[74:75], off
	global_load_dwordx4 v[242:245], v[76:77], off
	global_load_dwordx4 v[246:249], v[78:79], off
	s_branch .LBB0_15

.LBB0_15:
	v_ashrrev_i32_e32 v1, 31, v0
	v_lshlrev_b64 v[2:3], 12, v[0:1]
	v_lshl_add_u64 v[2:3], v[70:71], 0, v[2:3]
	global_load_dwordx2 v[64:65], v[2:3], off offset:512 nt
	global_load_dwordx2 v[66:67], v[2:3], off offset:1024 nt
	global_load_dwordx2 v[86:87], v[2:3], off offset:1536 nt
	v_add_u32_e32 v181, s55, v0
	global_load_dwordx2 v[88:89], v[2:3], off offset:2048 nt
	global_load_dwordx2 v[90:91], v[2:3], off offset:2560 nt
	v_cmp_gt_i32_e32 vcc, s76, v181
	s_waitcnt vmcnt(4)
	v_lshlrev_b32_e32 v162, 16, v64
	v_cndmask_b32_e32 v4, v0, v181, vcc
	v_ashrrev_i32_e32 v5, 31, v4
	v_lshlrev_b64 v[6:7], 12, v[4:5]
	v_lshlrev_b64 v[0:1], 13, v[0:1]
	v_lshl_add_u64 v[8:9], v[70:71], 0, v[6:7]
	v_lshl_add_u64 v[84:85], v[80:81], 0, v[0:1]
	global_load_dwordx2 v[92:93], v[8:9], off offset:512 nt
	global_load_dwordx2 v[94:95], v[8:9], off offset:1024 nt
	global_load_dwordx2 v[96:97], v[8:9], off offset:1536 nt
	global_load_dwordx2 v[100:101], v[8:9], off offset:2048 nt
	global_load_dwordx2 v[102:103], v[8:9], off offset:2560 nt
	global_load_dwordx2 v[170:171], v[2:3], off nt
	global_load_dwordx2 v[176:177], v[8:9], off nt
	global_load_dwordx4 v[56:59], v[84:85], off nt
	global_load_dwordx4 v[48:51], v[84:85], off offset:1024 nt
	global_load_dwordx4 v[40:43], v[84:85], off offset:2048 nt
	global_load_dwordx4 v[32:35], v[84:85], off offset:3072 nt
	global_load_dwordx2 v[110:111], v[2:3], off offset:3072 nt
	global_load_dwordx2 v[178:179], v[8:9], off offset:3072 nt
	global_load_dwordx2 v[182:183], v[2:3], off offset:3584 nt
	v_lshlrev_b64 v[0:1], 13, v[4:5]
	v_add_co_u32_e64 v4, s[10:11], s29, v84
	v_lshl_add_u64 v[82:83], v[80:81], 0, v[0:1]
	s_nop 0
	v_addc_co_u32_e64 v5, s[10:11], 0, v85, s[10:11]
	v_add_co_u32_e64 v0, s[10:11], s29, v82
	global_load_dwordx4 v[28:31], v[4:5], off nt
	global_load_dwordx4 v[20:23], v[4:5], off offset:1024 nt
	global_load_dwordx4 v[12:15], v[4:5], off offset:2048 nt
	s_nop 0
	global_load_dwordx4 v[4:7], v[4:5], off offset:3072 nt
	s_nop 0
	global_load_dwordx4 v[60:63], v[82:83], off nt
	global_load_dwordx4 v[52:55], v[82:83], off offset:1024 nt
	global_load_dwordx4 v[44:47], v[82:83], off offset:2048 nt
	global_load_dwordx4 v[36:39], v[82:83], off offset:3072 nt
	v_addc_co_u32_e64 v1, s[10:11], 0, v83, s[10:11]
	global_load_dwordx2 v[192:193], v[8:9], off offset:3584 nt
	global_load_dwordx4 v[24:27], v[0:1], off nt
	global_load_dwordx4 v[16:19], v[0:1], off offset:1024 nt
	s_nop 0
	global_load_dwordx4 v[8:11], v[0:1], off offset:2048 nt
	s_nop 0
	global_load_dwordx4 v[0:3], v[0:1], off offset:3072 nt
	s_waitcnt vmcnt(28)
	v_and_b32_e32 v99, 0xffff0000, v88
	s_waitcnt vmcnt(27)
	v_lshlrev_b32_e32 v98, 16, v90
	v_and_b32_e32 v117, 0xffff0000, v90
	v_mov_b32_e32 v116, v99
	v_and_b32_e32 v167, 0xffff0000, v64
	v_lshlrev_b32_e32 v164, 16, v65
	v_and_b32_e32 v169, 0xffff0000, v65
	v_lshlrev_b32_e32 v104, 16, v88
	v_lshlrev_b32_e32 v122, 16, v91
	v_mov_b32_e32 v105, v98
	v_pk_mul_f32 v[64:65], v[116:117], v[116:117]
	v_lshlrev_b32_e32 v108, 16, v89
	v_and_b32_e32 v125, 0xffff0000, v89
	v_pk_fma_f32 v[64:65], v[104:105], v[104:105], v[64:65]
	v_mov_b32_e32 v109, v122
	v_and_b32_e32 v133, 0xffff0000, v91
	v_pk_fma_f32 v[64:65], v[108:109], v[108:109], v[64:65]
	v_mov_b32_e32 v132, v125
	v_pk_fma_f32 v[194:195], v[132:133], v[132:133], v[64:65]
	v_lshlrev_b32_e32 v134, 16, v86
	v_and_b32_e32 v139, 0xffff0000, v86
	v_lshlrev_b32_e32 v136, 16, v87
	v_and_b32_e32 v141, 0xffff0000, v87
	v_lshlrev_b32_e32 v150, 16, v66
	v_and_b32_e32 v155, 0xffff0000, v66
	v_lshlrev_b32_e32 v152, 16, v67
	v_and_b32_e32 v157, 0xffff0000, v67
	v_mov_b32_e32 v175, v162
	v_mov_b32_e32 v173, v164
	v_mov_b32_e32 v161, v150
	v_mov_b32_e32 v159, v152
	v_mov_b32_e32 v145, v134
	v_mov_b32_e32 v143, v136
	s_waitcnt vmcnt(26)
	v_lshlrev_b32_e32 v174, 16, v92
	s_waitcnt vmcnt(25)
	v_lshlrev_b32_e32 v160, 16, v94
	s_waitcnt vmcnt(24)
	v_lshlrev_b32_e32 v144, 16, v96
	s_waitcnt vmcnt(23)
	v_and_b32_e32 v121, 0xffff0000, v100
	s_waitcnt vmcnt(22)
	v_lshlrev_b32_e32 v116, 16, v102
	v_and_b32_e32 v129, 0xffff0000, v102
	v_mov_b32_e32 v128, v121
	v_lshlrev_b32_e32 v114, 16, v100
	v_lshlrev_b32_e32 v120, 16, v103
	v_mov_b32_e32 v115, v116
	v_pk_mul_f32 v[64:65], v[128:129], v[128:129]
	v_lshlrev_b32_e32 v112, 16, v101
	v_and_b32_e32 v123, 0xffff0000, v101
	v_pk_fma_f32 v[64:65], v[114:115], v[114:115], v[64:65]
	v_mov_b32_e32 v113, v120
	s_waitcnt vmcnt(15)
	v_and_b32_e32 v119, 0xffff0000, v110
	v_and_b32_e32 v147, 0xffff0000, v96
	v_and_b32_e32 v131, 0xffff0000, v103
	v_pk_fma_f32 v[64:65], v[112:113], v[112:113], v[64:65]
	v_mov_b32_e32 v130, v123
	s_waitcnt vmcnt(13)
	v_lshlrev_b32_e32 v96, 16, v182
	v_and_b32_e32 v87, 0xffff0000, v182
	v_mov_b32_e32 v86, v119
	v_and_b32_e32 v135, 0xffff0000, v94
	v_pk_fma_f32 v[196:197], v[130:131], v[130:131], v[64:65]
	v_lshlrev_b32_e32 v106, 16, v110
	v_lshlrev_b32_e32 v94, 16, v183
	v_mov_b32_e32 v107, v96
	v_pk_mul_f32 v[64:65], v[86:87], v[86:87]
	v_lshlrev_b32_e32 v158, 16, v95
	v_and_b32_e32 v137, 0xffff0000, v95
	v_lshlrev_b32_e32 v110, 16, v111
	v_and_b32_e32 v127, 0xffff0000, v111
	v_and_b32_e32 v95, 0xffff0000, v178
	v_pk_fma_f32 v[64:65], v[106:107], v[106:107], v[64:65]
	v_mov_b32_e32 v111, v94
	v_and_b32_e32 v89, 0xffff0000, v183
	v_pk_fma_f32 v[64:65], v[110:111], v[110:111], v[64:65]
	v_mov_b32_e32 v88, v127
	s_waitcnt vmcnt(4)
	v_lshlrev_b32_e32 v86, 16, v192
	v_and_b32_e32 v91, 0xffff0000, v192
	v_mov_b32_e32 v90, v95
	v_lshlrev_b32_e32 v100, 16, v178
	v_pk_fma_f32 v[182:183], v[88:89], v[88:89], v[64:65]
	v_lshlrev_b32_e32 v88, 16, v193
	v_mov_b32_e32 v101, v86
	v_pk_mul_f32 v[64:65], v[90:91], v[90:91]
	v_lshlrev_b32_e32 v142, 16, v97
	v_and_b32_e32 v149, 0xffff0000, v97
	v_lshlrev_b32_e32 v102, 16, v179
	v_and_b32_e32 v97, 0xffff0000, v179
	v_pk_fma_f32 v[64:65], v[100:101], v[100:101], v[64:65]
	v_mov_b32_e32 v103, v88
	v_and_b32_e32 v151, 0xffff0000, v92
	v_lshlrev_b32_e32 v172, 16, v93
	v_and_b32_e32 v153, 0xffff0000, v93
	v_and_b32_e32 v93, 0xffff0000, v193
	v_pk_fma_f32 v[64:65], v[102:103], v[102:103], v[64:65]
	v_mov_b32_e32 v92, v97
	v_pk_fma_f32 v[192:193], v[92:93], v[92:93], v[64:65]
	v_and_b32_e32 v101, 0xffff0000, v176
	v_and_b32_e32 v199, 0xffff0000, v170
	v_lshlrev_b32_e32 v198, 16, v170
	v_mov_b32_e32 v166, v151
	v_mov_b32_e32 v206, v101
	v_mov_b32_e32 v207, v199
	v_lshlrev_b32_e32 v178, 16, v176
	v_lshlrev_b32_e32 v200, 16, v171
	v_and_b32_e32 v201, 0xffff0000, v171
	v_pk_mul_f32 v[170:171], v[166:167], v[166:167]
	v_mov_b32_e32 v154, v135
	v_mov_b32_e32 v179, v198
	v_pk_mul_f32 v[206:207], v[206:207], v[206:207]
	v_lshlrev_b32_e32 v176, 16, v177
	v_and_b32_e32 v103, 0xffff0000, v177
	v_pk_fma_f32 v[170:171], v[174:175], v[174:175], v[170:171]
	v_pk_mul_f32 v[202:203], v[154:155], v[154:155]
	v_mov_b32_e32 v138, v147
	v_pk_fma_f32 v[206:207], v[178:179], v[178:179], v[206:207]
	v_mov_b32_e32 v177, v200
	v_pk_fma_f32 v[170:171], v[172:173], v[172:173], v[170:171]
	v_mov_b32_e32 v168, v153
	v_pk_fma_f32 v[202:203], v[160:161], v[160:161], v[202:203]
	v_pk_mul_f32 v[204:205], v[138:139], v[138:139]
	v_mov_b32_e32 v208, v103
	v_mov_b32_e32 v209, v201
	v_pk_fma_f32 v[206:207], v[176:177], v[176:177], v[206:207]
	v_pk_fma_f32 v[170:171], v[168:169], v[168:169], v[170:171]
	v_pk_fma_f32 v[202:203], v[158:159], v[158:159], v[202:203]
	v_mov_b32_e32 v156, v137
	v_pk_fma_f32 v[204:205], v[144:145], v[144:145], v[204:205]
	v_pk_fma_f32 v[206:207], v[208:209], v[208:209], v[206:207]
	v_pk_fma_f32 v[202:203], v[156:157], v[156:157], v[202:203]
	v_pk_fma_f32 v[204:205], v[142:143], v[142:143], v[204:205]
	v_mov_b32_e32 v140, v149
	v_pk_add_f32 v[170:171], v[206:207], v[170:171]
	v_pk_fma_f32 v[204:205], v[140:141], v[140:141], v[204:205]
	v_pk_add_f32 v[170:171], v[170:171], v[202:203]
	v_mov_b32_e32 v202, v196
	v_pk_add_f32 v[170:171], v[170:171], v[204:205]
	v_mov_b32_e32 v203, v194
	v_pk_add_f32 v[170:171], v[170:171], v[202:203]
	v_mov_b32_e32 v194, v197
	v_pk_add_f32 v[170:171], v[170:171], v[194:195]
	v_mov_b32_e32 v194, v192
	v_mov_b32_e32 v195, v182
	v_pk_add_f32 v[170:171], v[170:171], v[194:195]
	v_mov_b32_e32 v182, v193
	v_pk_add_f32 v[170:171], v[170:171], v[182:183]
	ds_bpermute_b32 v182, v118, v170
	ds_bpermute_b32 v183, v118, v171
	s_waitcnt lgkmcnt(0)
	v_pk_add_f32 v[170:171], v[170:171], v[182:183]
	ds_bpermute_b32 v182, v124, v170
	ds_bpermute_b32 v183, v124, v171
	s_waitcnt lgkmcnt(0)
	v_pk_add_f32 v[170:171], v[170:171], v[182:183]
	ds_bpermute_b32 v182, v126, v170
	ds_bpermute_b32 v183, v126, v171
	s_waitcnt lgkmcnt(0)
	v_pk_add_f32 v[170:171], v[170:171], v[182:183]
	ds_bpermute_b32 v182, v146, v170
	ds_bpermute_b32 v183, v146, v171
	s_waitcnt lgkmcnt(0)
	v_pk_add_f32 v[170:171], v[170:171], v[182:183]
	ds_bpermute_b32 v182, v148, v170
	ds_bpermute_b32 v183, v148, v171
	s_waitcnt lgkmcnt(0)
	v_pk_add_f32 v[170:171], v[170:171], v[182:183]
	ds_bpermute_b32 v182, v180, v170
	ds_bpermute_b32 v183, v180, v171
	s_waitcnt lgkmcnt(0)
	v_pk_add_f32 v[170:171], v[170:171], v[182:183]
	s_nop 0
	v_pk_fma_f32 v[170:171], v[170:171], s[34:35], v[188:189] op_sel_hi:[1,0,0]
	s_nop 0
	v_mul_f32_e32 v90, 0x4b800000, v170
	v_cmp_gt_f32_e64 s[10:11], s80, v170
	v_mul_f32_e32 v92, 0x4b800000, v171
	v_cmp_gt_f32_e64 s[12:13], s80, v171
	v_cndmask_b32_e64 v90, v170, v90, s[10:11]
	v_rsq_f32_e32 v90, v90
	v_cndmask_b32_e64 v92, v171, v92, s[12:13]
	v_rsq_f32_e32 v92, v92
	v_mul_f32_e32 v105, 0x45800000, v90
	v_cndmask_b32_e64 v90, v90, v105, s[10:11]
	v_mul_f32_e32 v105, 0x45800000, v92
	v_cndmask_b32_e64 v170, v92, v105, s[12:13]
	v_pk_mul_f32 v[182:183], v[170:171], v[198:199] op_sel_hi:[0,1]
	s_waitcnt vmcnt(0)
	v_pk_fma_f32 v[56:57], v[210:211], v[182:183], v[56:57]
	v_pk_mul_f32 v[182:183], v[170:171], v[200:201] op_sel_hi:[0,1]
	v_pk_fma_f32 v[58:59], v[212:213], v[182:183], v[58:59]
	global_store_dwordx4 v[84:85], v[56:59], off nt
	s_and_saveexec_b64 s[4:5], vcc
	s_cbranch_execz .LBB0_17
	v_mov_b32_e32 v177, v103
	v_mov_b32_e32 v179, v101
	v_pk_mul_f32 v[56:57], v[90:91], v[178:179] op_sel_hi:[0,1]
	v_pk_mul_f32 v[58:59], v[90:91], v[176:177] op_sel_hi:[0,1]
	v_pk_fma_f32 v[56:57], v[210:211], v[56:57], v[60:61]
	v_pk_fma_f32 v[58:59], v[212:213], v[58:59], v[62:63]
	global_store_dwordx4 v[82:83], v[56:59], off nt
.LBB0_17:
	s_or_b64 exec, exec, s[4:5]
	v_mov_b32_e32 v171, v170
	v_mov_b32_e32 v163, v167
	v_mov_b32_e32 v165, v169
	v_pk_mul_f32 v[60:61], v[170:171], v[162:163]
	v_pk_mul_f32 v[62:63], v[170:171], v[164:165]
	v_pk_fma_f32 v[48:49], v[60:61], v[214:215], v[48:49]
	v_pk_fma_f32 v[50:51], v[62:63], v[216:217], v[50:51]
	global_store_dwordx4 v[84:85], v[48:51], off offset:1024 nt
	s_and_saveexec_b64 s[4:5], vcc
	s_cbranch_execz .LBB0_19
	v_mov_b32_e32 v175, v151
	v_mov_b32_e32 v173, v153
	v_pk_mul_f32 v[48:49], v[90:91], v[174:175] op_sel_hi:[0,1]
	v_pk_mul_f32 v[50:51], v[90:91], v[172:173] op_sel_hi:[0,1]
	v_pk_fma_f32 v[48:49], v[48:49], v[214:215], v[52:53]
	v_pk_fma_f32 v[50:51], v[50:51], v[216:217], v[54:55]
	global_store_dwordx4 v[82:83], v[48:51], off offset:1024 nt
.LBB0_19:
	s_or_b64 exec, exec, s[4:5]
	v_mov_b32_e32 v151, v155
	v_mov_b32_e32 v153, v157
	v_pk_mul_f32 v[52:53], v[170:171], v[150:151]
	v_pk_mul_f32 v[54:55], v[170:171], v[152:153]
	v_pk_fma_f32 v[40:41], v[52:53], v[218:219], v[40:41]
	v_pk_fma_f32 v[42:43], v[54:55], v[220:221], v[42:43]
	global_store_dwordx4 v[84:85], v[40:43], off offset:2048 nt
	s_and_saveexec_b64 s[4:5], vcc
	s_cbranch_execz .LBB0_21
	v_mov_b32_e32 v161, v135
	v_mov_b32_e32 v159, v137
	v_pk_mul_f32 v[40:41], v[90:91], v[160:161] op_sel_hi:[0,1]
	v_pk_mul_f32 v[42:43], v[90:91], v[158:159] op_sel_hi:[0,1]
	v_pk_fma_f32 v[40:41], v[40:41], v[218:219], v[44:45]
	v_pk_fma_f32 v[42:43], v[42:43], v[220:221], v[46:47]
	global_store_dwordx4 v[82:83], v[40:43], off offset:2048 nt
.LBB0_21:
	s_or_b64 exec, exec, s[4:5]
	v_mov_b32_e32 v135, v139
	v_mov_b32_e32 v137, v141
	v_pk_mul_f32 v[44:45], v[170:171], v[134:135]
	v_pk_mul_f32 v[46:47], v[170:171], v[136:137]
	v_pk_fma_f32 v[32:33], v[44:45], v[222:223], v[32:33]
	v_pk_fma_f32 v[34:35], v[46:47], v[224:225], v[34:35]
	global_store_dwordx4 v[84:85], v[32:35], off offset:3072 nt
	s_and_saveexec_b64 s[4:5], vcc
	s_cbranch_execz .LBB0_23
	v_mov_b32_e32 v145, v147
	v_mov_b32_e32 v143, v149
	v_pk_mul_f32 v[32:33], v[90:91], v[144:145] op_sel_hi:[0,1]
	v_pk_mul_f32 v[34:35], v[90:91], v[142:143] op_sel_hi:[0,1]
	v_pk_fma_f32 v[32:33], v[32:33], v[222:223], v[36:37]
	v_pk_fma_f32 v[34:35], v[34:35], v[224:225], v[38:39]
	global_store_dwordx4 v[82:83], v[32:35], off offset:3072 nt
.LBB0_23:
	s_or_b64 exec, exec, s[4:5]
	v_mov_b32_e32 v105, v99
	v_mov_b32_e32 v109, v125
	v_pk_mul_f32 v[38:39], v[170:171], v[104:105]
	v_pk_mul_f32 v[40:41], v[170:171], v[108:109]
	v_lshl_add_u64 v[36:37], v[84:85], 0, s[86:87]
	v_pk_fma_f32 v[28:29], v[38:39], v[234:235], v[28:29]
	v_pk_fma_f32 v[30:31], v[40:41], v[236:237], v[30:31]
	global_store_dwordx4 v[36:37], v[28:31], off nt
	s_and_saveexec_b64 s[4:5], vcc
	s_cbranch_execz .LBB0_25
	v_mov_b32_e32 v115, v121
	v_mov_b32_e32 v113, v123
	v_pk_mul_f32 v[30:31], v[90:91], v[114:115] op_sel_hi:[0,1]
	v_pk_fma_f32 v[24:25], v[30:31], v[234:235], v[24:25]
	v_pk_mul_f32 v[30:31], v[90:91], v[112:113] op_sel_hi:[0,1]
	v_lshl_add_u64 v[28:29], v[82:83], 0, s[86:87]
	v_pk_fma_f32 v[26:27], v[30:31], v[236:237], v[26:27]
	global_store_dwordx4 v[28:29], v[24:27], off nt
.LBB0_25:
	s_or_b64 exec, exec, s[4:5]
	v_mov_b32_e32 v99, v117
	v_mov_b32_e32 v123, v133
	s_mov_b64 s[4:5], 0x1400
	v_pk_mul_f32 v[30:31], v[170:171], v[98:99]
	v_pk_mul_f32 v[32:33], v[170:171], v[122:123]
	v_lshl_add_u64 v[28:29], v[84:85], 0, s[4:5]
	v_pk_fma_f32 v[20:21], v[30:31], v[238:239], v[20:21]
	v_pk_fma_f32 v[22:23], v[32:33], v[240:241], v[22:23]
	global_store_dwordx4 v[28:29], v[20:23], off nt
	s_and_saveexec_b64 s[4:5], vcc
	s_cbranch_execz .LBB0_27
	v_mov_b32_e32 v117, v129
	v_mov_b32_e32 v121, v131
	v_pk_mul_f32 v[22:23], v[90:91], v[116:117] op_sel_hi:[0,1]
	s_mov_b64 s[6:7], 0x1400
	v_pk_fma_f32 v[16:17], v[22:23], v[238:239], v[16:17]
	v_pk_mul_f32 v[22:23], v[90:91], v[120:121] op_sel_hi:[0,1]
	v_lshl_add_u64 v[20:21], v[82:83], 0, s[6:7]
	v_pk_fma_f32 v[18:19], v[22:23], v[240:241], v[18:19]
	global_store_dwordx4 v[20:21], v[16:19], off nt
.LBB0_27:
	s_or_b64 exec, exec, s[4:5]
	v_mov_b32_e32 v107, v119
	v_mov_b32_e32 v111, v127
	s_mov_b64 s[4:5], 0x1800
	v_pk_mul_f32 v[22:23], v[170:171], v[106:107]
	v_pk_mul_f32 v[24:25], v[170:171], v[110:111]
	v_lshl_add_u64 v[20:21], v[84:85], 0, s[4:5]
	v_pk_fma_f32 v[12:13], v[22:23], v[242:243], v[12:13]
	v_pk_fma_f32 v[14:15], v[24:25], v[244:245], v[14:15]
	global_store_dwordx4 v[20:21], v[12:15], off nt
	s_and_saveexec_b64 s[4:5], vcc
	s_cbranch_execz .LBB0_29
	v_mov_b32_e32 v101, v95
	v_mov_b32_e32 v103, v97
	v_pk_mul_f32 v[14:15], v[90:91], v[100:101] op_sel_hi:[0,1]
	s_mov_b64 s[6:7], 0x1800
	v_pk_fma_f32 v[8:9], v[14:15], v[242:243], v[8:9]
	v_pk_mul_f32 v[14:15], v[90:91], v[102:103] op_sel_hi:[0,1]
	v_lshl_add_u64 v[12:13], v[82:83], 0, s[6:7]
	v_pk_fma_f32 v[10:11], v[14:15], v[244:245], v[10:11]
	global_store_dwordx4 v[12:13], v[8:11], off nt
.LBB0_29:
	s_or_b64 exec, exec, s[4:5]
	v_mov_b32_e32 v97, v87
	v_mov_b32_e32 v95, v89
	v_pk_mul_f32 v[14:15], v[170:171], v[96:97]
	s_mov_b64 s[4:5], 0x1c00
	v_lshl_add_u64 v[12:13], v[84:85], 0, s[4:5]
	v_pk_fma_f32 v[4:5], v[14:15], v[246:247], v[4:5]
	v_pk_mul_f32 v[14:15], v[170:171], v[94:95]
	s_nop 0
	v_pk_fma_f32 v[6:7], v[14:15], v[248:249], v[6:7]
	global_store_dwordx4 v[12:13], v[4:7], off nt
	s_and_saveexec_b64 s[4:5], vcc
	s_cbranch_execz .LBB0_14
	v_mov_b32_e32 v87, v91
	v_mov_b32_e32 v89, v93
	v_pk_mul_f32 v[6:7], v[90:91], v[86:87] op_sel_hi:[0,1]
	s_mov_b64 s[6:7], 0x1c00
	v_pk_fma_f32 v[0:1], v[6:7], v[246:247], v[0:1]
	v_pk_mul_f32 v[6:7], v[90:91], v[88:89] op_sel_hi:[0,1]
	v_lshl_add_u64 v[4:5], v[82:83], 0, s[6:7]
	v_pk_fma_f32 v[2:3], v[6:7], v[248:249], v[2:3]
	global_store_dwordx4 v[4:5], v[0:3], off nt
	s_branch .LBB0_14

.LBB0_128:
	s_andn2_b64 vcc, exec, s[0:1]
	s_cbranch_vccnz .LBB0_165
	v_readfirstlane_b32 s2, v184
	v_readfirstlane_b32 s3, v185
	v_mov_b32_e32 v1, v189
	v_readlane_b32 s4, v254, 10
	v_readlane_b32 s5, v254, 11
	v_readlane_b32 s6, v254, 12
	v_readlane_b32 s7, v254, 13
	v_lshlrev_b32_e32 v2, 4, v189
	v_add_u32_e32 v3, 0x1000, v2
	global_load_dwordx4 v[4:7], v2, s[4:5]
	global_load_dwordx4 v[8:11], v3, s[4:5]
	global_load_dwordx4 v[12:15], v2, s[6:7]
	global_load_dwordx4 v[16:19], v3, s[6:7]
	s_waitcnt vmcnt(0)
	ds_write_b128 v2, v[4:7]
	ds_write_b128 v2, v[8:11] offset:4096
	ds_write_b128 v2, v[12:15] offset:8192
	ds_write_b128 v2, v[16:19] offset:12288
	s_waitcnt lgkmcnt(0)
	s_barrier
	s_nop 0
	v_ashrrev_i32_e32 v0, 6, v1
	s_waitcnt vmcnt(6)
	v_add_u32_e32 v132, s62, v0
	v_cmp_gt_i32_e32 vcc, s76, v132
	s_and_saveexec_b64 s[0:1], vcc
	s_cbranch_execz .LBB0_164
	v_and_b32_e32 v1, 63, v1
	v_cmp_lt_i32_e32 vcc, v228, v227
	v_lshlrev_b32_e32 v186, 4, v1
	v_lshlrev_b32_e32 v209, 4, v1
	v_lshlrev_b32_e32 v2, 3, v1
	v_cndmask_b32_e32 v1, v226, v228, vcc
	v_cmp_lt_i32_e32 vcc, v229, v227
	v_lshlrev_b32_e32 v134, 2, v1
	v_readlane_b32 s4, v254, 10
	v_cndmask_b32_e32 v1, v226, v229, vcc
	v_cmp_lt_i32_e32 vcc, v230, v227
	v_lshlrev_b32_e32 v158, 2, v1
	v_readlane_b32 s5, v254, 11
	v_cndmask_b32_e32 v1, v226, v230, vcc
	v_cmp_lt_i32_e32 vcc, v231, v227
	v_lshlrev_b32_e32 v160, 2, v1
	v_mov_b32_e32 v3, v187
	v_cndmask_b32_e32 v1, v226, v231, vcc
	v_cmp_lt_i32_e32 vcc, v232, v227
	v_lshlrev_b32_e32 v172, 2, v1
	v_lshl_add_u64 v[72:73], s[4:5], 0, v[186:187]
	v_cndmask_b32_e32 v1, v226, v232, vcc
	v_cmp_lt_i32_e32 vcc, v233, v227
	v_lshl_add_u64 v[4:5], s[2:3], 0, v[2:3]
	s_mov_b64 s[4:5], 0x8000000
	v_lshlrev_b32_e32 v174, 2, v1
	v_cndmask_b32_e32 v1, v226, v233, vcc
	v_readlane_b32 s6, v254, 12
	v_readlane_b32 s7, v254, 13
	v_lshl_add_u64 v[76:77], v[4:5], 0, s[4:5]
	v_lshlrev_b32_e32 v208, 2, v1
	s_mov_b64 s[4:5], 0x4000000
	v_ashrrev_i32_e32 v1, 31, v0
	v_lshl_add_u64 v[74:75], s[6:7], 0, v[186:187]
	v_lshl_add_u64 v[78:79], v[4:5], 0, s[4:5]
	s_mov_b64 s[4:5], 0x1400
	s_mov_b64 s[6:7], 0x1800
	v_lshl_add_u64 v[0:1], s[62:63], 0, v[0:1]
	v_lshl_add_u64 v[82:83], v[72:73], 0, s[4:5]
	v_lshl_add_u64 v[84:85], v[72:73], 0, s[6:7]
	v_lshl_add_u64 v[90:91], v[74:75], 0, s[4:5]
	v_lshl_add_u64 v[92:93], v[74:75], 0, s[6:7]
	v_readlane_b32 s4, v254, 2
	v_lshlrev_b64 v[4:5], 12, v[0:1]
	s_mov_b64 s[8:9], 0x1c00
	v_readlane_b32 s6, v254, 4
	v_readlane_b32 s7, v254, 5
	v_or_b32_e32 v4, v4, v2
	v_lshlrev_b64 v[0:1], 13, v[0:1]
	v_lshl_add_u64 v[80:81], v[72:73], 0, s[86:87]
	v_lshl_add_u64 v[86:87], v[72:73], 0, s[8:9]
	v_lshl_add_u64 v[88:89], v[74:75], 0, s[86:87]
	v_lshl_add_u64 v[94:95], v[74:75], 0, s[8:9]
	v_lshl_add_u64 v[96:97], s[72:73], 0, v[186:187]
	v_lshl_add_u64 v[98:99], s[6:7], 0, v[186:187]
	v_lshl_add_u64 v[100:101], s[2:3], 0, v[4:5]
	v_lshl_add_u64 v[102:103], s[6:7], 0, v[0:1]
	v_lshl_add_u64 v[104:105], s[72:73], 0, v[0:1]
	s_mov_b64 s[2:3], 0
	v_readlane_b32 s5, v254, 3
	s_branch .LBB0_132

.LBB0_132:
	v_add_co_u32_e32 v12, vcc, 0x8000000, v100
	v_add_u32_e32 v0, s55, v132
	s_nop 0
	v_addc_co_u32_e32 v13, vcc, 0, v101, vcc
	v_cmp_gt_i32_e64 s[10:11], s76, v0
	global_load_dwordx2 v[32:33], v[12:13], off offset:512 nt
	global_load_dwordx2 v[38:39], v[12:13], off offset:1024 nt
	global_load_dwordx2 v[108:109], v[12:13], off offset:1536 nt
	v_cndmask_b32_e64 v16, v132, v0, s[10:11]
	global_load_dwordx2 v[110:111], v[12:13], off offset:2048 nt
	v_ashrrev_i32_e32 v17, 31, v16
	v_lshlrev_b64 v[106:107], 12, v[16:17]
	v_lshl_add_u64 v[44:45], v[76:77], 0, v[106:107]
	global_load_dwordx2 v[112:113], v[44:45], off offset:512 nt
	global_load_dwordx2 v[114:115], v[44:45], off offset:1024 nt
	global_load_dwordx2 v[116:117], v[44:45], off offset:1536 nt
	global_load_dwordx2 v[118:119], v[44:45], off offset:2048 nt
	global_load_dwordx2 v[122:123], v[12:13], off offset:2560 nt
	global_load_dwordx2 v[124:125], v[44:45], off offset:2560 nt
	global_load_dwordx2 v[14:15], v[12:13], off nt
	global_load_dwordx2 v[120:121], v[44:45], off nt
	v_lshl_add_u64 v[18:19], v[104:105], 0, v[186:187]
	global_load_dwordx4 v[4:7], v[18:19], off nt
	global_load_dwordx4 v[0:3], v[18:19], off offset:1024 nt
	global_load_dwordx4 v[8:11], v[18:19], off offset:2048 nt
	global_load_dwordx4 v[20:23], v[18:19], off offset:3072 nt
	global_load_dwordx2 v[128:129], v[12:13], off offset:3072 nt
	v_add_co_u32_e32 v18, vcc, s29, v18
	s_waitcnt vmcnt(16)
	v_lshlrev_b32_e32 v198, 16, v32
	v_addc_co_u32_e32 v19, vcc, 0, v19, vcc
	global_load_dwordx2 v[136:137], v[44:45], off offset:3072 nt
	global_load_dwordx4 v[28:31], v[18:19], off nt
	global_load_dwordx4 v[40:43], v[18:19], off offset:1024 nt
	global_load_dwordx2 v[138:139], v[12:13], off offset:3584 nt
	global_load_dwordx4 v[48:51], v[18:19], off offset:2048 nt
	global_load_dwordx4 v[56:59], v[18:19], off offset:3072 nt
	v_lshlrev_b64 v[12:13], 13, v[16:17]
	v_lshl_add_u64 v[46:47], v[96:97], 0, v[12:13]
	v_add_co_u32_e32 v60, vcc, s29, v46
	global_load_dwordx4 v[16:19], v[46:47], off nt
	global_load_dwordx4 v[24:27], v[46:47], off offset:1024 nt
	global_load_dwordx4 v[68:71], v[46:47], off offset:2048 nt
	global_load_dwordx4 v[34:37], v[46:47], off offset:3072 nt
	v_addc_co_u32_e32 v61, vcc, 0, v47, vcc
	global_load_dwordx2 v[210:211], v[44:45], off offset:3584 nt
	s_nop 0
	global_load_dwordx4 v[44:47], v[60:61], off nt
	global_load_dwordx4 v[52:55], v[60:61], off offset:1024 nt
	global_load_dwordx4 v[64:67], v[60:61], off offset:2048 nt
	s_nop 0
	global_load_dwordx4 v[60:63], v[60:61], off offset:3072 nt
	s_waitcnt vmcnt(28)
	v_and_b32_e32 v141, 0xffff0000, v110
	s_waitcnt vmcnt(23)
	v_lshlrev_b32_e32 v140, 16, v122
	v_and_b32_e32 v143, 0xffff0000, v122
	v_mov_b32_e32 v142, v141
	v_and_b32_e32 v203, 0xffff0000, v32
	v_lshlrev_b32_e32 v32, 16, v108
	v_and_b32_e32 v167, 0xffff0000, v108
	v_lshlrev_b32_e32 v164, 16, v109
	v_and_b32_e32 v169, 0xffff0000, v109
	v_lshlrev_b32_e32 v152, 16, v110
	v_lshlrev_b32_e32 v144, 16, v123
	v_mov_b32_e32 v153, v140
	v_pk_mul_f32 v[108:109], v[142:143], v[142:143]
	v_lshlrev_b32_e32 v154, 16, v111
	v_and_b32_e32 v145, 0xffff0000, v111
	v_pk_fma_f32 v[108:109], v[152:153], v[152:153], v[108:109]
	v_mov_b32_e32 v155, v144
	v_and_b32_e32 v159, 0xffff0000, v118
	v_and_b32_e32 v147, 0xffff0000, v123
	v_pk_fma_f32 v[108:109], v[154:155], v[154:155], v[108:109]
	v_mov_b32_e32 v146, v145
	v_pk_fma_f32 v[122:123], v[146:147], v[146:147], v[108:109]
	s_waitcnt vmcnt(22)
	v_lshlrev_b32_e32 v146, 16, v124
	v_and_b32_e32 v149, 0xffff0000, v124
	v_mov_b32_e32 v148, v159
	v_lshlrev_b32_e32 v156, 16, v118
	v_lshlrev_b32_e32 v142, 16, v125
	v_mov_b32_e32 v157, v146
	v_pk_mul_f32 v[108:109], v[148:149], v[148:149]
	v_lshlrev_b32_e32 v178, 16, v38
	v_and_b32_e32 v183, 0xffff0000, v38
	v_lshlrev_b32_e32 v180, 16, v39
	v_and_b32_e32 v193, 0xffff0000, v39
	v_lshlrev_b32_e32 v38, 16, v119
	v_and_b32_e32 v161, 0xffff0000, v119
	v_pk_fma_f32 v[108:109], v[156:157], v[156:157], v[108:109]
	v_mov_b32_e32 v39, v142
	v_and_b32_e32 v151, 0xffff0000, v125
	v_pk_fma_f32 v[108:109], v[38:39], v[38:39], v[108:109]
	v_mov_b32_e32 v150, v161
	s_waitcnt vmcnt(15)
	v_and_b32_e32 v111, 0xffff0000, v128
	v_pk_fma_f32 v[214:215], v[150:151], v[150:151], v[108:109]
	v_mov_b32_e32 v108, v111
	v_lshlrev_b32_e32 v206, 16, v112
	v_and_b32_e32 v179, 0xffff0000, v112
	v_lshlrev_b32_e32 v170, 16, v116
	v_and_b32_e32 v173, 0xffff0000, v116
	v_lshlrev_b32_e32 v162, 16, v117
	v_and_b32_e32 v175, 0xffff0000, v117
	v_lshlrev_b32_e32 v126, 16, v128
	v_lshlrev_b32_e32 v196, 16, v113
	v_and_b32_e32 v181, 0xffff0000, v113
	v_lshlrev_b32_e32 v128, 16, v129
	v_and_b32_e32 v113, 0xffff0000, v129
	v_lshlrev_b32_e32 v200, 16, v33
	v_and_b32_e32 v205, 0xffff0000, v33
	v_lshlrev_b32_e32 v194, 16, v114
	v_and_b32_e32 v33, 0xffff0000, v114
	v_lshlrev_b32_e32 v176, 16, v115
	v_and_b32_e32 v165, 0xffff0000, v115
	v_mov_b32_e32 v114, v113
	v_and_b32_e32 v221, 0xffff0000, v120
	v_and_b32_e32 v239, 0xffff0000, v14
	v_lshlrev_b32_e32 v220, 16, v120
	v_lshlrev_b32_e32 v238, 16, v14
	v_mov_b32_e32 v202, v179
	s_waitcnt vmcnt(14)
	v_lshlrev_b32_e32 v130, 16, v136
	v_and_b32_e32 v133, 0xffff0000, v136
	v_lshlrev_b32_e32 v124, 16, v137
	s_waitcnt vmcnt(11)
	v_lshlrev_b32_e32 v110, 16, v138
	v_and_b32_e32 v109, 0xffff0000, v138
	v_lshlrev_b32_e32 v112, 16, v139
	v_mov_b32_e32 v127, v110
	v_pk_mul_f32 v[116:117], v[108:109], v[108:109]
	v_mov_b32_e32 v129, v112
	v_pk_fma_f32 v[116:117], v[126:127], v[126:127], v[116:117]
	v_and_b32_e32 v115, 0xffff0000, v139
	v_pk_fma_f32 v[116:117], v[128:129], v[128:129], v[116:117]
	v_and_b32_e32 v135, 0xffff0000, v137
	v_pk_fma_f32 v[136:137], v[114:115], v[114:115], v[116:117]
	s_waitcnt vmcnt(4)
	v_lshlrev_b32_e32 v114, 16, v210
	v_and_b32_e32 v117, 0xffff0000, v210
	v_lshlrev_b32_e32 v108, 16, v211
	v_and_b32_e32 v119, 0xffff0000, v211
	ds_read_b128 v[210:213], v209
	v_mov_b32_e32 v250, v221
	v_mov_b32_e32 v251, v239
	v_lshlrev_b32_e32 v216, 16, v121
	v_lshlrev_b32_e32 v218, 16, v15
	v_and_b32_e32 v219, 0xffff0000, v15
	v_mov_b32_e32 v207, v198
	v_pk_mul_f32 v[14:15], v[202:203], v[202:203]
	v_mov_b32_e32 v182, v33
	v_mov_b32_e32 v248, v220
	v_mov_b32_e32 v249, v238
	v_pk_mul_f32 v[250:251], v[250:251], v[250:251]
	v_and_b32_e32 v217, 0xffff0000, v121
	v_pk_fma_f32 v[14:15], v[206:207], v[206:207], v[14:15]
	v_mov_b32_e32 v197, v200
	v_mov_b32_e32 v195, v178
	v_pk_mul_f32 v[120:121], v[182:183], v[182:183]
	v_mov_b32_e32 v166, v173
	v_mov_b32_e32 v244, v216
	v_mov_b32_e32 v245, v218
	v_pk_fma_f32 v[248:249], v[248:249], v[248:249], v[250:251]
	v_pk_fma_f32 v[14:15], v[196:197], v[196:197], v[14:15]
	v_mov_b32_e32 v204, v181
	v_pk_fma_f32 v[120:121], v[194:195], v[194:195], v[120:121]
	v_mov_b32_e32 v177, v180
	v_mov_b32_e32 v171, v32
	v_pk_mul_f32 v[240:241], v[166:167], v[166:167]
	v_mov_b32_e32 v246, v217
	v_mov_b32_e32 v247, v219
	v_pk_fma_f32 v[244:245], v[244:245], v[244:245], v[248:249]
	v_mov_b32_e32 v116, v133
	v_pk_fma_f32 v[14:15], v[204:205], v[204:205], v[14:15]
	v_pk_fma_f32 v[120:121], v[176:177], v[176:177], v[120:121]
	v_mov_b32_e32 v192, v165
	v_pk_fma_f32 v[240:241], v[170:171], v[170:171], v[240:241]
	v_mov_b32_e32 v163, v164
	v_pk_fma_f32 v[244:245], v[246:247], v[246:247], v[244:245]
	v_mov_b32_e32 v131, v114
	v_pk_mul_f32 v[138:139], v[116:117], v[116:117]
	v_pk_fma_f32 v[120:121], v[192:193], v[192:193], v[120:121]
	v_pk_fma_f32 v[240:241], v[162:163], v[162:163], v[240:241]
	v_mov_b32_e32 v168, v175
	v_pk_add_f32 v[14:15], v[244:245], v[14:15]
	v_pk_fma_f32 v[138:139], v[130:131], v[130:131], v[138:139]
	v_mov_b32_e32 v125, v108
	v_pk_fma_f32 v[240:241], v[168:169], v[168:169], v[240:241]
	v_pk_add_f32 v[14:15], v[14:15], v[120:121]
	v_pk_fma_f32 v[138:139], v[124:125], v[124:125], v[138:139]
	v_mov_b32_e32 v118, v135
	v_pk_add_f32 v[14:15], v[14:15], v[240:241]
	v_mov_b32_e32 v120, v214
	v_mov_b32_e32 v121, v122
	v_pk_fma_f32 v[138:139], v[118:119], v[118:119], v[138:139]
	v_pk_add_f32 v[14:15], v[14:15], v[120:121]
	v_mov_b32_e32 v122, v215
	v_pk_add_f32 v[14:15], v[14:15], v[122:123]
	v_mov_b32_e32 v120, v138
	v_mov_b32_e32 v121, v136
	v_pk_add_f32 v[14:15], v[14:15], v[120:121]
	v_mov_b32_e32 v136, v139
	v_pk_add_f32 v[14:15], v[14:15], v[136:137]
	ds_bpermute_b32 v121, v134, v15
	ds_bpermute_b32 v120, v134, v14
	v_lshl_add_u64 v[122:123], v[102:103], 0, v[186:187]
	s_waitcnt lgkmcnt(0)
	v_pk_add_f32 v[14:15], v[14:15], v[120:121]
	ds_bpermute_b32 v121, v158, v15
	ds_bpermute_b32 v120, v158, v14
	s_waitcnt lgkmcnt(0)
	v_pk_add_f32 v[14:15], v[14:15], v[120:121]
	ds_bpermute_b32 v121, v160, v15
	ds_bpermute_b32 v120, v160, v14
	s_waitcnt lgkmcnt(0)
	v_pk_add_f32 v[14:15], v[14:15], v[120:121]
	ds_bpermute_b32 v121, v172, v15
	ds_bpermute_b32 v120, v172, v14
	s_waitcnt lgkmcnt(0)
	v_pk_add_f32 v[14:15], v[14:15], v[120:121]
	ds_bpermute_b32 v121, v174, v15
	ds_bpermute_b32 v120, v174, v14
	s_waitcnt lgkmcnt(0)
	v_pk_add_f32 v[14:15], v[14:15], v[120:121]
	ds_bpermute_b32 v121, v208, v15
	ds_bpermute_b32 v120, v208, v14
	s_waitcnt lgkmcnt(0)
	v_pk_add_f32 v[14:15], v[14:15], v[120:121]
	s_nop 0
	v_pk_fma_f32 v[14:15], v[14:15], s[34:35], v[188:189] op_sel_hi:[1,0,0]
	v_lshl_add_u64 v[120:121], v[98:99], 0, v[12:13]
	v_mul_f32_e32 v39, 0x4b800000, v15
	v_cmp_gt_f32_e32 vcc, s80, v15
	s_nop 1
	v_cndmask_b32_e32 v15, v15, v39, vcc
	v_rsq_f32_e32 v15, v15
	s_nop 0
	v_mul_f32_e32 v12, 0x45800000, v15
	v_cndmask_b32_e32 v138, v15, v12, vcc
	v_mul_f32_e32 v15, 0x4b800000, v14
	v_cmp_gt_f32_e32 vcc, s80, v14
	v_pk_mul_f32 v[12:13], v[138:139], v[238:239] op_sel_hi:[0,1]
	s_waitcnt vmcnt(0) lgkmcnt(0)
	v_pk_fma_f32 v[12:13], v[210:211], v[12:13], v[4:5]
	v_cndmask_b32_e32 v14, v14, v15, vcc
	v_rsq_f32_e32 v39, v14
	v_pk_mul_f32 v[14:15], v[138:139], v[218:219] op_sel_hi:[0,1]
	v_pk_fma_f32 v[14:15], v[212:213], v[14:15], v[6:7]
	global_store_dwordx4 v[122:123], v[12:15], off
	v_mul_f32_e32 v4, 0x45800000, v39
	v_cndmask_b32_e32 v136, v39, v4, vcc
	v_pk_mul_f32 v[4:5], v[136:137], v[220:221] op_sel_hi:[0,1]
	v_pk_mul_f32 v[6:7], v[136:137], v[216:217] op_sel_hi:[0,1]
	v_pk_fma_f32 v[4:5], v[210:211], v[4:5], v[16:17]
	v_pk_fma_f32 v[6:7], v[212:213], v[6:7], v[18:19]
	s_and_saveexec_b64 s[4:5], s[10:11]
	s_cbranch_execz .LBB0_134
	global_store_dwordx4 v[120:121], v[4:7], off
.LBB0_134:
	s_or_b64 exec, exec, s[4:5]
	v_mov_b32_e32 v139, v138
	v_mov_b32_e32 v199, v203
	v_mov_b32_e32 v201, v205
	v_pk_mul_f32 v[16:17], v[138:139], v[198:199]
	v_pk_mul_f32 v[18:19], v[138:139], v[200:201]
	ds_read_b128 v[198:201], v209 offset:1024
	v_mov_b32_e32 v137, v136
	v_mov_b32_e32 v207, v179
	v_mov_b32_e32 v197, v181
	v_pk_mul_f32 v[202:203], v[136:137], v[206:207]
	s_waitcnt lgkmcnt(0)
	v_pk_fma_f32 v[16:17], v[16:17], v[198:199], v[0:1]
	v_pk_fma_f32 v[0:1], v[202:203], v[198:199], v[24:25]
	v_pk_mul_f32 v[24:25], v[136:137], v[196:197]
	v_pk_fma_f32 v[18:19], v[18:19], v[200:201], v[2:3]
	v_pk_fma_f32 v[2:3], v[24:25], v[200:201], v[26:27]
	global_store_dwordx4 v[122:123], v[16:19], off offset:1024
	s_and_saveexec_b64 s[4:5], s[10:11]
	s_cbranch_execz .LBB0_136
	global_store_dwordx4 v[120:121], v[0:3], off offset:1024
.LBB0_136:
	s_or_b64 exec, exec, s[4:5]
	v_mov_b32_e32 v179, v183
	v_mov_b32_e32 v181, v193
	v_pk_mul_f32 v[24:25], v[138:139], v[178:179]
	v_pk_mul_f32 v[26:27], v[138:139], v[180:181]
	ds_read_b128 v[178:181], v209 offset:2048
	v_mov_b32_e32 v195, v33
	v_mov_b32_e32 v177, v165
	v_pk_mul_f32 v[182:183], v[136:137], v[194:195]
	s_waitcnt lgkmcnt(0)
	v_pk_fma_f32 v[24:25], v[24:25], v[178:179], v[8:9]
	v_pk_fma_f32 v[8:9], v[182:183], v[178:179], v[68:69]
	v_pk_mul_f32 v[68:69], v[136:137], v[176:177]
	v_pk_fma_f32 v[26:27], v[26:27], v[180:181], v[10:11]
	v_pk_fma_f32 v[10:11], v[68:69], v[180:181], v[70:71]
	global_store_dwordx4 v[122:123], v[24:27], off offset:2048
	s_and_saveexec_b64 s[4:5], s[10:11]
	s_cbranch_execz .LBB0_138
	global_store_dwordx4 v[120:121], v[8:11], off offset:2048
.LBB0_138:
	s_or_b64 exec, exec, s[4:5]
	ds_read_b128 v[68:71], v209 offset:3072
	v_mov_b32_e32 v33, v167
	v_mov_b32_e32 v171, v173
	v_mov_b32_e32 v165, v169
	v_mov_b32_e32 v163, v175
	v_pk_mul_f32 v[32:33], v[138:139], v[32:33]
	v_pk_mul_f32 v[166:167], v[136:137], v[170:171]
	v_pk_mul_f32 v[164:165], v[138:139], v[164:165]
	s_waitcnt lgkmcnt(0)
	v_pk_fma_f32 v[32:33], v[32:33], v[68:69], v[20:21]
	v_pk_fma_f32 v[20:21], v[166:167], v[68:69], v[34:35]
	v_pk_mul_f32 v[68:69], v[136:137], v[162:163]
	v_pk_fma_f32 v[34:35], v[164:165], v[70:71], v[22:23]
	v_pk_fma_f32 v[22:23], v[68:69], v[70:71], v[36:37]
	global_store_dwordx4 v[122:123], v[32:35], off offset:3072
	s_and_saveexec_b64 s[4:5], s[10:11]
	s_cbranch_execz .LBB0_140
	global_store_dwordx4 v[120:121], v[20:23], off offset:3072
.LBB0_140:
	s_or_b64 exec, exec, s[4:5]
	ds_read_b128 v[68:71], v209 offset:4096
	v_mov_b32_e32 v153, v141
	v_mov_b32_e32 v155, v145
	v_mov_b32_e32 v157, v159
	v_mov_b32_e32 v39, v161
	v_pk_mul_f32 v[36:37], v[138:139], v[152:153]
	v_pk_mul_f32 v[152:153], v[138:139], v[154:155]
	v_pk_mul_f32 v[154:155], v[136:137], v[156:157]
	s_waitcnt lgkmcnt(0)
	v_pk_fma_f32 v[36:37], v[36:37], v[68:69], v[28:29]
	v_pk_fma_f32 v[28:29], v[154:155], v[68:69], v[44:45]
	v_pk_mul_f32 v[44:45], v[136:137], v[38:39]
	v_pk_fma_f32 v[38:39], v[152:153], v[70:71], v[30:31]
	v_pk_fma_f32 v[30:31], v[44:45], v[70:71], v[46:47]
	v_add_co_u32_e32 v44, vcc, 0x1000, v122
	s_nop 1
	v_addc_co_u32_e32 v45, vcc, 0, v123, vcc
	global_store_dwordx4 v[44:45], v[36:39], off
	s_and_saveexec_b64 s[4:5], s[10:11]
	s_cbranch_execz .LBB0_142
	v_add_co_u32_e32 v44, vcc, 0x1000, v120
	s_nop 1
	v_addc_co_u32_e32 v45, vcc, 0, v121, vcc
	global_store_dwordx4 v[44:45], v[28:31], off
.LBB0_142:
	s_or_b64 exec, exec, s[4:5]
	ds_read_b128 v[68:71], v209 offset:5120
	v_mov_b32_e32 v141, v143
	v_mov_b32_e32 v145, v147
	v_mov_b32_e32 v147, v149
	v_mov_b32_e32 v143, v151
	v_pk_mul_f32 v[44:45], v[138:139], v[140:141]
	v_pk_mul_f32 v[140:141], v[136:137], v[146:147]
	v_pk_mul_f32 v[46:47], v[138:139], v[144:145]
	s_waitcnt lgkmcnt(0)
	v_pk_fma_f32 v[44:45], v[44:45], v[68:69], v[40:41]
	v_pk_fma_f32 v[40:41], v[140:141], v[68:69], v[52:53]
	v_pk_mul_f32 v[52:53], v[136:137], v[142:143]
	v_pk_fma_f32 v[46:47], v[46:47], v[70:71], v[42:43]
	v_pk_fma_f32 v[42:43], v[52:53], v[70:71], v[54:55]
	v_add_co_u32_e32 v52, vcc, 0x1000, v122
	s_nop 1
	v_addc_co_u32_e32 v53, vcc, 0, v123, vcc
	global_store_dwordx4 v[52:53], v[44:47], off offset:1024
	s_and_saveexec_b64 s[4:5], s[10:11]
	s_cbranch_execz .LBB0_144
	v_add_co_u32_e32 v52, vcc, 0x1000, v120
	s_nop 1
	v_addc_co_u32_e32 v53, vcc, 0, v121, vcc
	global_store_dwordx4 v[52:53], v[40:43], off offset:1024
.LBB0_144:
	s_or_b64 exec, exec, s[4:5]
	ds_read_b128 v[68:71], v209 offset:6144
	v_mov_b32_e32 v127, v111
	v_mov_b32_e32 v131, v133
	v_mov_b32_e32 v129, v113
	v_mov_b32_e32 v125, v135
	v_pk_mul_f32 v[52:53], v[138:139], v[126:127]
	v_pk_mul_f32 v[126:127], v[136:137], v[130:131]
	v_pk_mul_f32 v[54:55], v[138:139], v[128:129]
	s_waitcnt lgkmcnt(0)
	v_pk_fma_f32 v[52:53], v[52:53], v[68:69], v[48:49]
	v_pk_fma_f32 v[48:49], v[126:127], v[68:69], v[64:65]
	v_pk_mul_f32 v[64:65], v[136:137], v[124:125]
	v_pk_fma_f32 v[54:55], v[54:55], v[70:71], v[50:51]
	v_pk_fma_f32 v[50:51], v[64:65], v[70:71], v[66:67]
	v_add_co_u32_e32 v64, vcc, 0x1000, v122
	s_nop 1
	v_addc_co_u32_e32 v65, vcc, 0, v123, vcc
	global_store_dwordx4 v[64:65], v[52:55], off offset:2048
	s_and_saveexec_b64 s[4:5], s[10:11]
	s_cbranch_execz .LBB0_146
	v_add_co_u32_e32 v64, vcc, 0x1000, v120
	s_nop 1
	v_addc_co_u32_e32 v65, vcc, 0, v121, vcc
	global_store_dwordx4 v[64:65], v[48:51], off offset:2048
.LBB0_146:
	s_or_b64 exec, exec, s[4:5]
	ds_read_b128 v[66:69], v209 offset:7168
	v_mov_b32_e32 v111, v109
	v_mov_b32_e32 v113, v115
	v_mov_b32_e32 v115, v117
	v_mov_b32_e32 v109, v119
	v_pk_mul_f32 v[64:65], v[138:139], v[110:111]
	v_pk_mul_f32 v[110:111], v[136:137], v[114:115]
	v_pk_mul_f32 v[70:71], v[138:139], v[112:113]
	s_waitcnt lgkmcnt(0)
	v_pk_fma_f32 v[64:65], v[64:65], v[66:67], v[56:57]
	v_pk_fma_f32 v[56:57], v[110:111], v[66:67], v[60:61]
	v_pk_mul_f32 v[60:61], v[136:137], v[108:109]
	v_pk_fma_f32 v[66:67], v[70:71], v[68:69], v[58:59]
	v_pk_fma_f32 v[58:59], v[60:61], v[68:69], v[62:63]
	v_add_co_u32_e32 v60, vcc, 0x1000, v122
	s_nop 1
	v_addc_co_u32_e32 v61, vcc, 0, v123, vcc
	global_store_dwordx4 v[60:61], v[64:67], off offset:3072
	s_and_saveexec_b64 s[4:5], s[10:11]
	s_cbranch_execz .LBB0_148
	v_add_co_u32_e32 v60, vcc, 0x1000, v120
	s_nop 1
	v_addc_co_u32_e32 v61, vcc, 0, v121, vcc
	global_store_dwordx4 v[60:61], v[56:59], off offset:3072
.LBB0_148:
	s_or_b64 exec, exec, s[4:5]
	v_mov_b32_e32 v62, v5
	v_mov_b32_e32 v63, v13
	v_mov_b32_e32 v60, v4
	v_mov_b32_e32 v61, v12
	v_pk_mul_f32 v[62:63], v[62:63], v[62:63]
	v_mov_b32_e32 v68, v1
	v_pk_fma_f32 v[60:61], v[60:61], v[60:61], v[62:63]
	v_mov_b32_e32 v62, v6
	v_mov_b32_e32 v63, v14
	v_pk_fma_f32 v[60:61], v[62:63], v[62:63], v[60:61]
	v_mov_b32_e32 v62, v7
	v_mov_b32_e32 v63, v15
	v_mov_b32_e32 v69, v17
	v_pk_fma_f32 v[60:61], v[62:63], v[62:63], v[60:61]
	v_mov_b32_e32 v62, v0
	v_mov_b32_e32 v63, v16
	v_pk_mul_f32 v[68:69], v[68:69], v[68:69]
	v_pk_mul_f32 v[70:71], v[56:57], v[56:57]
	v_pk_fma_f32 v[62:63], v[62:63], v[62:63], v[68:69]
	v_mov_b32_e32 v68, v2
	v_mov_b32_e32 v69, v18
	v_pk_fma_f32 v[62:63], v[68:69], v[68:69], v[62:63]
	v_mov_b32_e32 v68, v3
	v_mov_b32_e32 v69, v19
	v_pk_fma_f32 v[62:63], v[68:69], v[68:69], v[62:63]
	v_mov_b32_e32 v68, v9
	v_mov_b32_e32 v69, v25
	v_pk_add_f32 v[60:61], v[60:61], v[62:63]
	v_mov_b32_e32 v62, v8
	v_mov_b32_e32 v63, v24
	v_pk_mul_f32 v[68:69], v[68:69], v[68:69]
	v_mov_b32_e32 v108, v70
	v_pk_fma_f32 v[62:63], v[62:63], v[62:63], v[68:69]
	v_mov_b32_e32 v68, v10
	v_mov_b32_e32 v69, v26
	v_pk_fma_f32 v[62:63], v[68:69], v[68:69], v[62:63]
	v_mov_b32_e32 v68, v11
	v_mov_b32_e32 v69, v27
	v_pk_fma_f32 v[62:63], v[68:69], v[68:69], v[62:63]
	v_mov_b32_e32 v68, v21
	v_mov_b32_e32 v69, v33
	v_pk_add_f32 v[60:61], v[60:61], v[62:63]
	v_mov_b32_e32 v62, v20
	v_mov_b32_e32 v63, v32
	v_pk_mul_f32 v[68:69], v[68:69], v[68:69]
	s_nop 0
	v_pk_fma_f32 v[62:63], v[62:63], v[62:63], v[68:69]
	v_mov_b32_e32 v68, v22
	v_mov_b32_e32 v69, v34
	v_pk_fma_f32 v[62:63], v[68:69], v[68:69], v[62:63]
	v_mov_b32_e32 v68, v23
	v_mov_b32_e32 v69, v35
	v_pk_fma_f32 v[62:63], v[68:69], v[68:69], v[62:63]
	v_mov_b32_e32 v68, v29
	v_mov_b32_e32 v69, v37
	v_pk_add_f32 v[60:61], v[60:61], v[62:63]
	v_mov_b32_e32 v62, v28
	v_mov_b32_e32 v63, v36
	v_pk_mul_f32 v[68:69], v[68:69], v[68:69]
	s_nop 0
	v_pk_fma_f32 v[62:63], v[62:63], v[62:63], v[68:69]
	v_mov_b32_e32 v68, v30
	v_mov_b32_e32 v69, v38
	v_pk_fma_f32 v[62:63], v[68:69], v[68:69], v[62:63]
	v_mov_b32_e32 v68, v31
	v_mov_b32_e32 v69, v39
	v_pk_fma_f32 v[62:63], v[68:69], v[68:69], v[62:63]
	v_mov_b32_e32 v68, v41
	v_mov_b32_e32 v69, v45
	v_pk_add_f32 v[60:61], v[60:61], v[62:63]
	v_mov_b32_e32 v62, v40
	v_mov_b32_e32 v63, v44
	v_pk_mul_f32 v[68:69], v[68:69], v[68:69]
	s_nop 0
	v_pk_fma_f32 v[62:63], v[62:63], v[62:63], v[68:69]
	v_mov_b32_e32 v68, v42
	v_mov_b32_e32 v69, v46
	v_pk_fma_f32 v[62:63], v[68:69], v[68:69], v[62:63]
	v_mov_b32_e32 v68, v43
	v_mov_b32_e32 v69, v47
	v_pk_fma_f32 v[62:63], v[68:69], v[68:69], v[62:63]
	v_mov_b32_e32 v68, v49
	v_mov_b32_e32 v69, v53
	v_pk_add_f32 v[60:61], v[60:61], v[62:63]
	v_mov_b32_e32 v62, v48
	v_mov_b32_e32 v63, v52
	v_pk_mul_f32 v[68:69], v[68:69], v[68:69]
	s_nop 0
	v_pk_fma_f32 v[62:63], v[62:63], v[62:63], v[68:69]
	v_mov_b32_e32 v68, v50
	v_mov_b32_e32 v69, v54
	v_pk_fma_f32 v[62:63], v[68:69], v[68:69], v[62:63]
	v_mov_b32_e32 v68, v51
	v_mov_b32_e32 v69, v55
	v_pk_fma_f32 v[62:63], v[68:69], v[68:69], v[62:63]
	v_pk_mul_f32 v[68:69], v[66:67], v[66:67]
	v_pk_add_f32 v[60:61], v[60:61], v[62:63]
	v_pk_mul_f32 v[62:63], v[64:65], v[64:65]
	s_nop 0
	v_mov_b32_e32 v109, v62
	v_mov_b32_e32 v62, v71
	v_pk_mul_f32 v[70:71], v[58:59], v[58:59]
	v_pk_add_f32 v[62:63], v[108:109], v[62:63]
	v_mov_b32_e32 v108, v70
	v_mov_b32_e32 v109, v68
	v_pk_add_f32 v[62:63], v[62:63], v[108:109]
	v_mov_b32_e32 v68, v71
	v_pk_add_f32 v[62:63], v[68:69], v[62:63]
	v_lshl_add_u64 v[68:69], v[78:79], 0, v[106:107]
	v_pk_add_f32 v[60:61], v[60:61], v[62:63]
	ds_bpermute_b32 v63, v134, v61
	ds_bpermute_b32 v62, v134, v60
	s_waitcnt lgkmcnt(0)
	v_pk_add_f32 v[60:61], v[60:61], v[62:63]
	ds_bpermute_b32 v63, v158, v61
	ds_bpermute_b32 v62, v158, v60
	s_waitcnt lgkmcnt(0)
	v_pk_add_f32 v[60:61], v[60:61], v[62:63]
	ds_bpermute_b32 v63, v160, v61
	ds_bpermute_b32 v62, v160, v60
	s_waitcnt lgkmcnt(0)
	v_pk_add_f32 v[60:61], v[60:61], v[62:63]
	ds_bpermute_b32 v63, v172, v61
	ds_bpermute_b32 v62, v172, v60
	s_waitcnt lgkmcnt(0)
	v_pk_add_f32 v[60:61], v[60:61], v[62:63]
	ds_bpermute_b32 v63, v174, v61
	ds_bpermute_b32 v62, v174, v60
	s_waitcnt lgkmcnt(0)
	v_pk_add_f32 v[60:61], v[60:61], v[62:63]
	ds_bpermute_b32 v63, v208, v61
	ds_bpermute_b32 v62, v208, v60
	s_waitcnt lgkmcnt(0)
	v_pk_add_f32 v[60:61], v[60:61], v[62:63]
	s_nop 0
	v_pk_fma_f32 v[60:61], v[60:61], s[34:35], v[188:189] op_sel_hi:[1,0,0]
	s_nop 0
	v_mul_f32_e32 v62, 0x4b800000, v61
	v_cmp_gt_f32_e64 s[12:13], s80, v61
	v_cmp_gt_f32_e32 vcc, s80, v60
	s_nop 0
	v_cndmask_b32_e64 v61, v61, v62, s[12:13]
	v_rsq_f32_e32 v61, v61
	s_nop 0
	v_mul_f32_e32 v62, 0x45800000, v61
	v_cndmask_b32_e64 v108, v61, v62, s[12:13]
	v_mul_f32_e32 v61, 0x4b800000, v60
	v_cndmask_b32_e32 v60, v60, v61, vcc
	v_rsq_f32_e32 v60, v60
	v_pk_mul_f32 v[12:13], v[12:13], v[108:109] op_sel_hi:[1,0]
	v_pk_mul_f32 v[14:15], v[14:15], v[108:109] op_sel_hi:[1,0]
	v_mul_f32_e32 v61, 0x45800000, v60
	v_cndmask_b32_e32 v70, v60, v61, vcc
	ds_read_b128 v[60:63], v209 offset:8192
	s_waitcnt lgkmcnt(0)
	v_pk_mul_f32 v[12:13], v[60:61], v[12:13]
	v_pk_mul_f32 v[14:15], v[62:63], v[14:15]
	v_cvt_pk_bf16_f32 v12, v12, v13
	v_cvt_pk_bf16_f32 v13, v14, v15
	v_add_co_u32_e32 v14, vcc, 0x4000000, v100
	s_nop 1
	v_addc_co_u32_e32 v15, vcc, 0, v101, vcc
	global_store_dwordx2 v[14:15], v[12:13], off
	s_and_saveexec_b64 s[4:5], s[10:11]
	s_cbranch_execz .LBB0_150
	v_pk_mul_f32 v[4:5], v[4:5], v[70:71] op_sel_hi:[1,0]
	v_pk_mul_f32 v[6:7], v[6:7], v[70:71] op_sel_hi:[1,0]
	v_pk_mul_f32 v[4:5], v[60:61], v[4:5]
	v_pk_mul_f32 v[6:7], v[62:63], v[6:7]
	v_cvt_pk_bf16_f32 v4, v4, v5
	v_cvt_pk_bf16_f32 v5, v6, v7
	global_store_dwordx2 v[68:69], v[4:5], off
.LBB0_150:
	s_or_b64 exec, exec, s[4:5]
	ds_read_b128 v[4:7], v209 offset:9216
	v_mov_b32_e32 v109, v108
	v_pk_mul_f32 v[12:13], v[16:17], v[108:109]
	v_pk_mul_f32 v[14:15], v[18:19], v[108:109]
	s_waitcnt lgkmcnt(0)
	v_pk_mul_f32 v[12:13], v[12:13], v[4:5]
	v_pk_mul_f32 v[14:15], v[14:15], v[6:7]
	v_cvt_pk_bf16_f32 v12, v12, v13
	v_cvt_pk_bf16_f32 v13, v14, v15
	v_add_co_u32_e32 v14, vcc, 0x4000000, v100
	s_nop 1
	v_addc_co_u32_e32 v15, vcc, 0, v101, vcc
	global_store_dwordx2 v[14:15], v[12:13], off offset:512
	s_and_saveexec_b64 s[4:5], s[10:11]
	s_cbranch_execz .LBB0_152
	v_pk_mul_f32 v[0:1], v[0:1], v[70:71] op_sel_hi:[1,0]
	v_pk_mul_f32 v[2:3], v[2:3], v[70:71] op_sel_hi:[1,0]
	v_pk_mul_f32 v[0:1], v[0:1], v[4:5]
	v_pk_mul_f32 v[2:3], v[2:3], v[6:7]
	v_cvt_pk_bf16_f32 v0, v0, v1
	v_cvt_pk_bf16_f32 v1, v2, v3
	global_store_dwordx2 v[68:69], v[0:1], off offset:512
.LBB0_152:
	s_or_b64 exec, exec, s[4:5]
	ds_read_b128 v[0:3], v209 offset:10240
	v_pk_mul_f32 v[4:5], v[24:25], v[108:109]
	v_pk_mul_f32 v[6:7], v[26:27], v[108:109]
	s_waitcnt lgkmcnt(0)
	v_pk_mul_f32 v[4:5], v[4:5], v[0:1]
	v_pk_mul_f32 v[6:7], v[6:7], v[2:3]
	v_cvt_pk_bf16_f32 v4, v4, v5
	v_cvt_pk_bf16_f32 v5, v6, v7
	v_add_co_u32_e32 v6, vcc, 0x4000000, v100
	s_nop 1
	v_addc_co_u32_e32 v7, vcc, 0, v101, vcc
	global_store_dwordx2 v[6:7], v[4:5], off offset:1024
	s_and_saveexec_b64 s[4:5], s[10:11]
	s_cbranch_execz .LBB0_154
	v_pk_mul_f32 v[4:5], v[8:9], v[70:71] op_sel_hi:[1,0]
	s_nop 0
	v_pk_mul_f32 v[0:1], v[4:5], v[0:1]
	v_pk_mul_f32 v[4:5], v[10:11], v[70:71] op_sel_hi:[1,0]
	v_cvt_pk_bf16_f32 v0, v0, v1
	v_pk_mul_f32 v[2:3], v[4:5], v[2:3]
	s_nop 0
	v_cvt_pk_bf16_f32 v1, v2, v3
	global_store_dwordx2 v[68:69], v[0:1], off offset:1024
.LBB0_154:
	s_or_b64 exec, exec, s[4:5]
	ds_read_b128 v[0:3], v209 offset:11264
	v_pk_mul_f32 v[4:5], v[32:33], v[108:109]
	v_pk_mul_f32 v[6:7], v[34:35], v[108:109]
	s_waitcnt lgkmcnt(0)
	v_pk_mul_f32 v[4:5], v[4:5], v[0:1]
	v_pk_mul_f32 v[6:7], v[6:7], v[2:3]
	v_cvt_pk_bf16_f32 v4, v4, v5
	v_cvt_pk_bf16_f32 v5, v6, v7
	v_add_co_u32_e32 v6, vcc, 0x4000000, v100
	s_nop 1
	v_addc_co_u32_e32 v7, vcc, 0, v101, vcc
	global_store_dwordx2 v[6:7], v[4:5], off offset:1536
	s_and_saveexec_b64 s[4:5], s[10:11]
	s_cbranch_execz .LBB0_156
	v_pk_mul_f32 v[4:5], v[20:21], v[70:71] op_sel_hi:[1,0]
	s_nop 0
	v_pk_mul_f32 v[0:1], v[4:5], v[0:1]
	v_pk_mul_f32 v[4:5], v[22:23], v[70:71] op_sel_hi:[1,0]
	v_cvt_pk_bf16_f32 v0, v0, v1
	v_pk_mul_f32 v[2:3], v[4:5], v[2:3]
	s_nop 0
	v_cvt_pk_bf16_f32 v1, v2, v3
	global_store_dwordx2 v[68:69], v[0:1], off offset:1536
.LBB0_156:
	s_or_b64 exec, exec, s[4:5]
	ds_read_b128 v[0:3], v209 offset:12288
	v_pk_mul_f32 v[4:5], v[36:37], v[108:109]
	v_pk_mul_f32 v[6:7], v[38:39], v[108:109]
	s_waitcnt lgkmcnt(0)
	v_pk_mul_f32 v[4:5], v[4:5], v[0:1]
	v_pk_mul_f32 v[6:7], v[6:7], v[2:3]
	v_cvt_pk_bf16_f32 v4, v4, v5
	v_cvt_pk_bf16_f32 v5, v6, v7
	v_add_co_u32_e32 v6, vcc, 0x4000000, v100
	s_nop 1
	v_addc_co_u32_e32 v7, vcc, 0, v101, vcc
	global_store_dwordx2 v[6:7], v[4:5], off offset:2048
	s_and_saveexec_b64 s[4:5], s[10:11]
	s_cbranch_execz .LBB0_158
	v_pk_mul_f32 v[4:5], v[28:29], v[70:71] op_sel_hi:[1,0]
	s_nop 0
	v_pk_mul_f32 v[0:1], v[4:5], v[0:1]
	v_pk_mul_f32 v[4:5], v[30:31], v[70:71] op_sel_hi:[1,0]
	v_cvt_pk_bf16_f32 v0, v0, v1
	v_pk_mul_f32 v[2:3], v[4:5], v[2:3]
	s_nop 0
	v_cvt_pk_bf16_f32 v1, v2, v3
	global_store_dwordx2 v[68:69], v[0:1], off offset:2048
.LBB0_158:
	s_or_b64 exec, exec, s[4:5]
	ds_read_b128 v[0:3], v209 offset:13312
	v_pk_mul_f32 v[4:5], v[44:45], v[108:109]
	v_pk_mul_f32 v[6:7], v[46:47], v[108:109]
	s_waitcnt lgkmcnt(0)
	v_pk_mul_f32 v[4:5], v[4:5], v[0:1]
	v_pk_mul_f32 v[6:7], v[6:7], v[2:3]
	v_cvt_pk_bf16_f32 v4, v4, v5
	v_cvt_pk_bf16_f32 v5, v6, v7
	v_add_co_u32_e32 v6, vcc, 0x4000000, v100
	s_nop 1
	v_addc_co_u32_e32 v7, vcc, 0, v101, vcc
	global_store_dwordx2 v[6:7], v[4:5], off offset:2560
	s_and_saveexec_b64 s[4:5], s[10:11]
	s_cbranch_execz .LBB0_160
	v_pk_mul_f32 v[4:5], v[40:41], v[70:71] op_sel_hi:[1,0]
	s_nop 0
	v_pk_mul_f32 v[0:1], v[4:5], v[0:1]
	v_pk_mul_f32 v[4:5], v[42:43], v[70:71] op_sel_hi:[1,0]
	v_cvt_pk_bf16_f32 v0, v0, v1
	v_pk_mul_f32 v[2:3], v[4:5], v[2:3]
	s_nop 0
	v_cvt_pk_bf16_f32 v1, v2, v3
	global_store_dwordx2 v[68:69], v[0:1], off offset:2560
.LBB0_160:
	s_or_b64 exec, exec, s[4:5]
	ds_read_b128 v[0:3], v209 offset:14336
	v_pk_mul_f32 v[4:5], v[52:53], v[108:109]
	v_pk_mul_f32 v[6:7], v[54:55], v[108:109]
	s_waitcnt lgkmcnt(0)
	v_pk_mul_f32 v[4:5], v[4:5], v[0:1]
	v_pk_mul_f32 v[6:7], v[6:7], v[2:3]
	v_cvt_pk_bf16_f32 v4, v4, v5
	v_cvt_pk_bf16_f32 v5, v6, v7
	v_add_co_u32_e32 v6, vcc, 0x4000000, v100
	s_nop 1
	v_addc_co_u32_e32 v7, vcc, 0, v101, vcc
	global_store_dwordx2 v[6:7], v[4:5], off offset:3072
	s_and_saveexec_b64 s[4:5], s[10:11]
	s_cbranch_execz .LBB0_162
	v_pk_mul_f32 v[4:5], v[48:49], v[70:71] op_sel_hi:[1,0]
	s_nop 0
	v_pk_mul_f32 v[0:1], v[4:5], v[0:1]
	v_pk_mul_f32 v[4:5], v[50:51], v[70:71] op_sel_hi:[1,0]
	v_cvt_pk_bf16_f32 v0, v0, v1
	v_pk_mul_f32 v[2:3], v[4:5], v[2:3]
	s_nop 0
	v_cvt_pk_bf16_f32 v1, v2, v3
	global_store_dwordx2 v[68:69], v[0:1], off offset:3072
.LBB0_162:
	s_or_b64 exec, exec, s[4:5]
	ds_read_b128 v[0:3], v209 offset:15360
	v_pk_mul_f32 v[4:5], v[64:65], v[108:109]
	v_pk_mul_f32 v[6:7], v[66:67], v[108:109]
	v_add_co_u32_e32 v8, vcc, 0x4000000, v100
	s_waitcnt lgkmcnt(0)
	v_pk_mul_f32 v[4:5], v[4:5], v[0:1]
	v_pk_mul_f32 v[6:7], v[6:7], v[2:3]
	v_cvt_pk_bf16_f32 v4, v4, v5
	v_cvt_pk_bf16_f32 v5, v6, v7
	v_addc_co_u32_e32 v9, vcc, 0, v101, vcc
	global_store_dwordx2 v[8:9], v[4:5], off offset:3584
	s_and_saveexec_b64 s[4:5], s[10:11]
	s_cbranch_execz .LBB0_131
	v_pk_mul_f32 v[4:5], v[56:57], v[70:71] op_sel_hi:[1,0]
	s_nop 0
	v_pk_mul_f32 v[0:1], v[4:5], v[0:1]
	v_pk_mul_f32 v[4:5], v[58:59], v[70:71] op_sel_hi:[1,0]
	v_cvt_pk_bf16_f32 v0, v0, v1
	v_pk_mul_f32 v[2:3], v[4:5], v[2:3]
	s_nop 0
	v_cvt_pk_bf16_f32 v1, v2, v3
	global_store_dwordx2 v[68:69], v[0:1], off offset:3584
	s_branch .LBB0_131

.LBB0_258:
	s_andn2_b64 vcc, exec, s[0:1]
	s_cbranch_vccnz .LBB0_261
	s_cmpk_gt_u32 s39, 0xb7f
	s_cbranch_scc1 .LBB0_261
	v_add_u32_e32 v0, s38, v89
	v_add_u32_e32 v86, 0xffffe200, v0
	v_add_u32_e32 v80, 0xfffff200, v0
	v_ashrrev_i32_e32 v87, 31, v86
	v_lshlrev_b64 v[0:1], 13, v[86:87]
	v_ashrrev_i32_e32 v81, 31, v80
	v_lshl_add_u64 v[0:1], v[68:69], 0, v[0:1]
	v_lshlrev_b64 v[2:3], 13, v[80:81]
	v_lshl_add_u64 v[2:3], v[68:69], 0, v[2:3]
	global_load_dwordx4 v[104:107], v[70:71], off
	global_load_dwordx4 v[108:111], v[70:71], off offset:1024
	global_load_dwordx4 v[112:115], v[70:71], off offset:2048
	global_load_dwordx4 v[116:119], v[70:71], off offset:3072
	global_load_dwordx4 v[120:123], v[72:73], off
	global_load_dwordx4 v[124:127], v[74:75], off
	global_load_dwordx4 v[128:131], v[76:77], off
	global_load_dwordx4 v[132:135], v[78:79], off
	global_load_dwordx4 v[60:63], v[0:1], off nt
	global_load_dwordx4 v[56:59], v[2:3], off nt
	global_load_dwordx4 v[52:55], v[0:1], off offset:1024 nt
	global_load_dwordx4 v[48:51], v[2:3], off offset:1024 nt
	global_load_dwordx4 v[44:47], v[0:1], off offset:2048 nt
	global_load_dwordx4 v[40:43], v[2:3], off offset:2048 nt
	global_load_dwordx4 v[36:39], v[0:1], off offset:3072 nt
	global_load_dwordx4 v[32:35], v[2:3], off offset:3072 nt
	v_add_co_u32_e32 v0, vcc, s29, v0
	v_lshlrev_b64 v[86:87], 12, v[86:87]
	s_nop 0
	v_addc_co_u32_e32 v1, vcc, 0, v1, vcc
	global_load_dwordx4 v[28:31], v[0:1], off nt
	v_add_co_u32_e32 v2, vcc, s29, v2
	v_lshlrev_b64 v[80:81], 12, v[80:81]
	s_nop 0
	v_addc_co_u32_e32 v3, vcc, 0, v3, vcc
	global_load_dwordx4 v[24:27], v[2:3], off nt
	global_load_dwordx4 v[20:23], v[0:1], off offset:1024 nt
	global_load_dwordx4 v[16:19], v[2:3], off offset:1024 nt
	global_load_dwordx4 v[12:15], v[0:1], off offset:2048 nt
	global_load_dwordx4 v[8:11], v[2:3], off offset:2048 nt
	global_load_dwordx4 v[4:7], v[0:1], off offset:3072 nt
	s_nop 0
	global_load_dwordx4 v[0:3], v[2:3], off offset:3072 nt
	v_cmp_lt_i32_e32 vcc, v228, v227
	v_lshl_add_u64 v[86:87], v[66:67], 0, v[86:87]
	v_lshl_add_u64 v[80:81], v[66:67], 0, v[80:81]
	s_waitcnt vmcnt(15)
	v_mov_b32_e32 v95, v61
	s_waitcnt vmcnt(14)
	v_mov_b32_e32 v94, v57
	v_pk_mul_f32 v[94:95], v[94:95], v[94:95]
	s_waitcnt vmcnt(12)
	v_mov_b32_e32 v96, v49
	v_mov_b32_e32 v97, v53
	v_pk_mul_f32 v[96:97], v[96:97], v[96:97]
	s_waitcnt vmcnt(7)
	v_mov_b32_e32 v84, v29
	s_waitcnt vmcnt(5)
	v_mov_b32_e32 v85, v21
	v_mov_b32_e32 v82, v28
	v_mov_b32_e32 v83, v20
	v_pk_mul_f32 v[84:85], v[84:85], v[84:85]
	v_mov_b32_e32 v92, v25
	v_pk_fma_f32 v[82:83], v[82:83], v[82:83], v[84:85]
	v_mov_b32_e32 v84, v30
	v_mov_b32_e32 v85, v22
	v_pk_fma_f32 v[82:83], v[84:85], v[84:85], v[82:83]
	v_mov_b32_e32 v84, v31
	v_mov_b32_e32 v85, v23
	s_waitcnt vmcnt(4)
	v_mov_b32_e32 v93, v17
	v_pk_fma_f32 v[82:83], v[84:85], v[84:85], v[82:83]
	v_mov_b32_e32 v84, v24
	v_mov_b32_e32 v85, v16
	v_pk_mul_f32 v[92:93], v[92:93], v[92:93]
	s_waitcnt vmcnt(2)
	v_mov_b32_e32 v98, v9
	v_pk_fma_f32 v[84:85], v[84:85], v[84:85], v[92:93]
	v_mov_b32_e32 v92, v26
	v_mov_b32_e32 v93, v18
	v_pk_fma_f32 v[84:85], v[92:93], v[92:93], v[84:85]
	v_mov_b32_e32 v92, v27
	v_mov_b32_e32 v93, v19
	v_pk_fma_f32 v[84:85], v[92:93], v[92:93], v[84:85]
	v_mov_b32_e32 v92, v56
	v_mov_b32_e32 v93, v60
	v_pk_fma_f32 v[92:93], v[92:93], v[92:93], v[94:95]
	v_mov_b32_e32 v94, v58
	v_mov_b32_e32 v95, v62
	v_pk_fma_f32 v[92:93], v[94:95], v[94:95], v[92:93]
	v_mov_b32_e32 v94, v59
	v_mov_b32_e32 v95, v63
	v_pk_fma_f32 v[92:93], v[94:95], v[94:95], v[92:93]
	v_mov_b32_e32 v94, v48
	v_mov_b32_e32 v95, v52
	v_pk_fma_f32 v[94:95], v[94:95], v[94:95], v[96:97]
	v_mov_b32_e32 v96, v50
	v_mov_b32_e32 v97, v54
	v_pk_fma_f32 v[94:95], v[96:97], v[96:97], v[94:95]
	v_mov_b32_e32 v96, v51
	v_mov_b32_e32 v97, v55
	v_pk_fma_f32 v[94:95], v[96:97], v[96:97], v[94:95]
	v_mov_b32_e32 v96, v41
	v_mov_b32_e32 v97, v45
	v_pk_add_f32 v[92:93], v[92:93], v[94:95]
	v_mov_b32_e32 v94, v40
	v_mov_b32_e32 v95, v44
	v_pk_mul_f32 v[96:97], v[96:97], v[96:97]
	s_waitcnt vmcnt(0)
	v_mov_b32_e32 v99, v1
	v_pk_fma_f32 v[94:95], v[94:95], v[94:95], v[96:97]
	v_mov_b32_e32 v96, v42
	v_mov_b32_e32 v97, v46
	v_pk_fma_f32 v[94:95], v[96:97], v[96:97], v[94:95]
	v_mov_b32_e32 v96, v43
	v_mov_b32_e32 v97, v47
	v_pk_fma_f32 v[94:95], v[96:97], v[96:97], v[94:95]
	v_mov_b32_e32 v96, v33
	v_mov_b32_e32 v97, v37
	v_pk_add_f32 v[92:93], v[92:93], v[94:95]
	v_mov_b32_e32 v94, v32
	v_mov_b32_e32 v95, v36
	v_pk_mul_f32 v[96:97], v[96:97], v[96:97]
	v_pk_mul_f32 v[98:99], v[98:99], v[98:99]
	v_pk_fma_f32 v[94:95], v[94:95], v[94:95], v[96:97]
	v_mov_b32_e32 v96, v34
	v_mov_b32_e32 v97, v38
	v_pk_fma_f32 v[94:95], v[96:97], v[96:97], v[94:95]
	v_mov_b32_e32 v96, v35
	v_mov_b32_e32 v97, v39
	v_pk_fma_f32 v[94:95], v[96:97], v[96:97], v[94:95]
	v_mov_b32_e32 v96, v13
	v_pk_add_f32 v[92:93], v[92:93], v[94:95]
	v_mov_b32_e32 v94, v84
	v_mov_b32_e32 v95, v82
	v_mov_b32_e32 v97, v5
	v_pk_add_f32 v[92:93], v[92:93], v[94:95]
	v_mov_b32_e32 v94, v12
	v_mov_b32_e32 v95, v4
	v_pk_mul_f32 v[96:97], v[96:97], v[96:97]
	v_cndmask_b32_e32 v82, v226, v228, vcc
	v_pk_fma_f32 v[94:95], v[94:95], v[94:95], v[96:97]
	v_mov_b32_e32 v96, v14
	v_mov_b32_e32 v97, v6
	v_pk_fma_f32 v[94:95], v[96:97], v[96:97], v[94:95]
	v_mov_b32_e32 v96, v15
	v_mov_b32_e32 v97, v7
	v_pk_fma_f32 v[94:95], v[96:97], v[96:97], v[94:95]
	v_mov_b32_e32 v96, v8
	v_mov_b32_e32 v97, v0
	v_pk_fma_f32 v[96:97], v[96:97], v[96:97], v[98:99]
	v_mov_b32_e32 v98, v10
	v_mov_b32_e32 v99, v2
	v_cmp_lt_i32_e32 vcc, v229, v227
	v_pk_fma_f32 v[96:97], v[98:99], v[98:99], v[96:97]
	v_mov_b32_e32 v98, v11
	v_mov_b32_e32 v99, v3
	v_lshlrev_b32_e32 v91, 2, v82
	v_cndmask_b32_e32 v82, v226, v229, vcc
	v_cmp_lt_i32_e32 vcc, v230, v227
	v_pk_fma_f32 v[96:97], v[98:99], v[98:99], v[96:97]
	v_lshlrev_b32_e32 v98, 2, v82
	v_cndmask_b32_e32 v82, v226, v230, vcc
	v_cmp_lt_i32_e32 vcc, v231, v227
	v_lshlrev_b32_e32 v99, 2, v82
	v_mov_b32_e32 v84, v96
	v_cndmask_b32_e32 v82, v226, v231, vcc
	v_cmp_lt_i32_e32 vcc, v232, v227
	v_lshlrev_b32_e32 v100, 2, v82
	s_nop 0
	v_cndmask_b32_e32 v82, v226, v232, vcc
	v_cmp_lt_i32_e32 vcc, v233, v227
	v_lshlrev_b32_e32 v101, 2, v82
	s_nop 0
	v_cndmask_b32_e32 v82, v226, v233, vcc
	v_lshlrev_b32_e32 v102, 2, v82
	v_mov_b32_e32 v82, v85
	v_pk_add_f32 v[82:83], v[92:93], v[82:83]
	v_mov_b32_e32 v85, v94
	v_pk_add_f32 v[82:83], v[82:83], v[84:85]
	v_mov_b32_e32 v94, v97
	v_pk_add_f32 v[82:83], v[82:83], v[94:95]
	ds_bpermute_b32 v85, v91, v83
	ds_bpermute_b32 v84, v91, v82
	s_waitcnt lgkmcnt(0)
	v_pk_add_f32 v[82:83], v[82:83], v[84:85]
	ds_bpermute_b32 v85, v98, v83
	ds_bpermute_b32 v84, v98, v82
	s_waitcnt lgkmcnt(0)
	v_pk_add_f32 v[82:83], v[82:83], v[84:85]
	ds_bpermute_b32 v85, v99, v83
	ds_bpermute_b32 v84, v99, v82
	s_waitcnt lgkmcnt(0)
	v_pk_add_f32 v[82:83], v[82:83], v[84:85]
	ds_bpermute_b32 v85, v100, v83
	ds_bpermute_b32 v84, v100, v82
	s_waitcnt lgkmcnt(0)
	v_pk_add_f32 v[82:83], v[82:83], v[84:85]
	ds_bpermute_b32 v85, v101, v83
	ds_bpermute_b32 v84, v101, v82
	s_waitcnt lgkmcnt(0)
	v_pk_add_f32 v[82:83], v[82:83], v[84:85]
	ds_bpermute_b32 v85, v102, v83
	ds_bpermute_b32 v84, v102, v82
	s_waitcnt lgkmcnt(0)
	v_pk_add_f32 v[82:83], v[82:83], v[84:85]
	s_nop 0
	v_pk_fma_f32 v[82:83], v[82:83], s[34:35], v[188:189] op_sel_hi:[1,0,0]
	s_nop 0
	v_mul_f32_e32 v84, 0x4b800000, v83
	v_cmp_gt_f32_e64 s[10:11], s80, v83
	v_cmp_gt_f32_e32 vcc, s80, v82
	s_nop 0
	v_cndmask_b32_e64 v83, v83, v84, s[10:11]
	v_rsq_f32_e32 v83, v83
	s_nop 0
	v_mul_f32_e32 v84, 0x45800000, v83
	v_cndmask_b32_e64 v84, v83, v84, s[10:11]
	v_mul_f32_e32 v83, 0x4b800000, v82
	v_cndmask_b32_e32 v82, v82, v83, vcc
	v_rsq_f32_e32 v82, v82
	v_pk_mul_f32 v[60:61], v[60:61], v[84:85] op_sel_hi:[1,0]
	v_pk_mul_f32 v[62:63], v[62:63], v[84:85] op_sel_hi:[1,0]
	v_pk_mul_f32 v[52:53], v[52:53], v[84:85] op_sel_hi:[1,0]
	v_mul_f32_e32 v83, 0x45800000, v82
	v_cndmask_b32_e32 v82, v82, v83, vcc
	v_pk_mul_f32 v[56:57], v[56:57], v[82:83] op_sel_hi:[1,0]
	v_pk_mul_f32 v[58:59], v[58:59], v[82:83] op_sel_hi:[1,0]
	v_pk_mul_f32 v[54:55], v[54:55], v[84:85] op_sel_hi:[1,0]
	v_pk_mul_f32 v[48:49], v[48:49], v[82:83] op_sel_hi:[1,0]
	v_pk_mul_f32 v[50:51], v[50:51], v[82:83] op_sel_hi:[1,0]
	v_pk_mul_f32 v[44:45], v[44:45], v[84:85] op_sel_hi:[1,0]
	v_pk_mul_f32 v[46:47], v[46:47], v[84:85] op_sel_hi:[1,0]
	v_pk_mul_f32 v[40:41], v[40:41], v[82:83] op_sel_hi:[1,0]
	v_pk_mul_f32 v[42:43], v[42:43], v[82:83] op_sel_hi:[1,0]
	v_pk_mul_f32 v[36:37], v[36:37], v[84:85] op_sel_hi:[1,0]
	v_pk_mul_f32 v[38:39], v[38:39], v[84:85] op_sel_hi:[1,0]
	v_pk_mul_f32 v[32:33], v[32:33], v[82:83] op_sel_hi:[1,0]
	v_pk_mul_f32 v[34:35], v[34:35], v[82:83] op_sel_hi:[1,0]
	v_pk_mul_f32 v[28:29], v[28:29], v[84:85] op_sel_hi:[1,0]
	v_pk_mul_f32 v[30:31], v[30:31], v[84:85] op_sel_hi:[1,0]
	v_pk_mul_f32 v[24:25], v[24:25], v[82:83] op_sel_hi:[1,0]
	s_waitcnt vmcnt(0)
	v_pk_mul_f32 v[60:61], v[104:105], v[60:61]
	v_pk_mul_f32 v[62:63], v[106:107], v[62:63]
	v_pk_mul_f32 v[56:57], v[104:105], v[56:57]
	v_pk_mul_f32 v[58:59], v[106:107], v[58:59]
	v_cvt_pk_bf16_f32 v60, v60, v61
	v_cvt_pk_bf16_f32 v61, v62, v63
	v_cvt_pk_bf16_f32 v56, v56, v57
	v_cvt_pk_bf16_f32 v57, v58, v59
	global_store_dwordx2 v[86:87], v[60:61], off
	global_store_dwordx2 v[80:81], v[56:57], off
	v_pk_mul_f32 v[26:27], v[26:27], v[82:83] op_sel_hi:[1,0]
	v_pk_mul_f32 v[20:21], v[20:21], v[84:85] op_sel_hi:[1,0]
	v_pk_mul_f32 v[22:23], v[22:23], v[84:85] op_sel_hi:[1,0]
	v_pk_mul_f32 v[16:17], v[16:17], v[82:83] op_sel_hi:[1,0]
	v_pk_mul_f32 v[18:19], v[18:19], v[82:83] op_sel_hi:[1,0]
	v_pk_mul_f32 v[12:13], v[12:13], v[84:85] op_sel_hi:[1,0]
	v_pk_mul_f32 v[14:15], v[14:15], v[84:85] op_sel_hi:[1,0]
	v_pk_mul_f32 v[8:9], v[8:9], v[82:83] op_sel_hi:[1,0]
	v_pk_mul_f32 v[10:11], v[10:11], v[82:83] op_sel_hi:[1,0]
	v_pk_mul_f32 v[4:5], v[4:5], v[84:85] op_sel_hi:[1,0]
	v_pk_mul_f32 v[6:7], v[6:7], v[84:85] op_sel_hi:[1,0]
	v_pk_mul_f32 v[0:1], v[0:1], v[82:83] op_sel_hi:[1,0]
	v_pk_mul_f32 v[2:3], v[2:3], v[82:83] op_sel_hi:[1,0]
	v_pk_mul_f32 v[52:53], v[52:53], v[108:109]
	v_pk_mul_f32 v[54:55], v[54:55], v[110:111]
	v_pk_mul_f32 v[48:49], v[108:109], v[48:49]
	v_pk_mul_f32 v[50:51], v[50:51], v[110:111]
	v_cvt_pk_bf16_f32 v52, v52, v53
	v_cvt_pk_bf16_f32 v53, v54, v55
	v_cvt_pk_bf16_f32 v48, v48, v49
	v_cvt_pk_bf16_f32 v49, v50, v51
	global_store_dwordx2 v[86:87], v[52:53], off offset:512
	global_store_dwordx2 v[80:81], v[48:49], off offset:512
	v_pk_mul_f32 v[44:45], v[44:45], v[112:113]
	v_pk_mul_f32 v[46:47], v[46:47], v[114:115]
	v_pk_mul_f32 v[40:41], v[40:41], v[112:113]
	v_pk_mul_f32 v[42:43], v[42:43], v[114:115]
	v_cvt_pk_bf16_f32 v44, v44, v45
	v_cvt_pk_bf16_f32 v45, v46, v47
	v_cvt_pk_bf16_f32 v40, v40, v41
	v_cvt_pk_bf16_f32 v41, v42, v43
	global_store_dwordx2 v[86:87], v[44:45], off offset:1024
	global_store_dwordx2 v[80:81], v[40:41], off offset:1024
	v_pk_mul_f32 v[36:37], v[36:37], v[116:117]
	v_pk_mul_f32 v[38:39], v[38:39], v[118:119]
	v_pk_mul_f32 v[32:33], v[32:33], v[116:117]
	v_pk_mul_f32 v[34:35], v[34:35], v[118:119]
	v_cvt_pk_bf16_f32 v36, v36, v37
	v_cvt_pk_bf16_f32 v37, v38, v39
	v_cvt_pk_bf16_f32 v32, v32, v33
	v_cvt_pk_bf16_f32 v33, v34, v35
	global_store_dwordx2 v[86:87], v[36:37], off offset:1536
	global_store_dwordx2 v[80:81], v[32:33], off offset:1536
	v_pk_mul_f32 v[28:29], v[28:29], v[120:121]
	v_pk_mul_f32 v[30:31], v[30:31], v[122:123]
	v_pk_mul_f32 v[24:25], v[24:25], v[120:121]
	v_pk_mul_f32 v[26:27], v[26:27], v[122:123]
	v_cvt_pk_bf16_f32 v28, v28, v29
	v_cvt_pk_bf16_f32 v29, v30, v31
	v_cvt_pk_bf16_f32 v24, v24, v25
	v_cvt_pk_bf16_f32 v25, v26, v27
	global_store_dwordx2 v[86:87], v[28:29], off offset:2048
	global_store_dwordx2 v[80:81], v[24:25], off offset:2048
	v_pk_mul_f32 v[20:21], v[20:21], v[124:125]
	v_pk_mul_f32 v[22:23], v[22:23], v[126:127]
	v_pk_mul_f32 v[16:17], v[16:17], v[124:125]
	v_pk_mul_f32 v[18:19], v[18:19], v[126:127]
	v_cvt_pk_bf16_f32 v20, v20, v21
	v_cvt_pk_bf16_f32 v21, v22, v23
	v_cvt_pk_bf16_f32 v16, v16, v17
	v_cvt_pk_bf16_f32 v17, v18, v19
	global_store_dwordx2 v[86:87], v[20:21], off offset:2560
	global_store_dwordx2 v[80:81], v[16:17], off offset:2560
	v_pk_mul_f32 v[12:13], v[12:13], v[128:129]
	v_pk_mul_f32 v[14:15], v[14:15], v[130:131]
	v_pk_mul_f32 v[8:9], v[8:9], v[128:129]
	v_pk_mul_f32 v[10:11], v[10:11], v[130:131]
	v_cvt_pk_bf16_f32 v12, v12, v13
	v_cvt_pk_bf16_f32 v13, v14, v15
	v_cvt_pk_bf16_f32 v8, v8, v9
	v_cvt_pk_bf16_f32 v9, v10, v11
	global_store_dwordx2 v[86:87], v[12:13], off offset:3072
	global_store_dwordx2 v[80:81], v[8:9], off offset:3072
	v_pk_mul_f32 v[4:5], v[4:5], v[132:133]
	v_pk_mul_f32 v[6:7], v[6:7], v[134:135]
	v_pk_mul_f32 v[0:1], v[0:1], v[132:133]
	v_pk_mul_f32 v[2:3], v[2:3], v[134:135]
	v_cvt_pk_bf16_f32 v4, v4, v5
	v_cvt_pk_bf16_f32 v5, v6, v7
	v_cvt_pk_bf16_f32 v0, v0, v1
	v_cvt_pk_bf16_f32 v1, v2, v3
	global_store_dwordx2 v[86:87], v[4:5], off offset:3584
	global_store_dwordx2 v[80:81], v[0:1], off offset:3584
